# v23: v22 + write-through (sc1) stores for the f32 residual stream in the residual epilogues
# baseline (speedup 1.0000x reference)
; #define PG8_LAS __attribute__((address_space(3)))
; __device__ __forceinline__ unsigned cvt_pk_bf16(float lo, float hi) { unsigned r; asm volatile("v_cvt_pk_bf16_f32 %0, %1, %2" : "=v"(r) : "v"(lo), "v"(hi)); return r; }
; __device__ __forceinline__ float bperm(float v, int srclane) { return __int_as_float(__builtin_amdgcn_ds_bpermute(srclane << 2, __float_as_int(v))); }
; __device__ __forceinline__ float bperm(float v, int srclane) { return __int_as_float(__builtin_amdgcn_ds_bpermute(srclane << 2, __float_as_int(v))); }
;     __device__ __forceinline__ void fused(f32x4 (&acc)[2][2][4][2], const Unit& u, int wr, int wc, int fr, int fq, PG8_LAS unsigned char* lds, int wid, int lane) const {
;         float scl = scale; asm volatile("" : "+v"(scl)); const int row0 = u.pm * BM + wr * 64 + fr, col0 = u.pn * BM + wc * 32 + 4 * fq;
;         PG8_LAS float* P = (PG8_LAS float*)lds;
; #pragma unroll
;         for (int ai = 0; ai < 2; ++ai) { f32x4 xv[4][2][2];
; #pragma unroll
;             for (int m = 0; m < 4; ++m)
; #pragma unroll
;                 for (int bj = 0; bj < 2; ++bj)
; #pragma unroll
;                     for (int n = 0; n < 2; ++n) xv[m][bj][n] = *(const f32x4*)(xin + (size_t)(row0 + ai * HALF + m * 16) * 1024 + col0 + bj * HALF + n * 16);
;             __builtin_amdgcn_sched_barrier(0);
; #pragma unroll
;             for (int m = 0; m < 4; ++m) { const int row = row0 + ai * HALF + m * 16; float q = 0.f;
; #pragma unroll
;                 for (int bj = 0; bj < 2; ++bj)
; #pragma unroll
;                     for (int n = 0; n < 2; ++n) { const size_t off = (size_t)row * 1024 + col0 + bj * HALF + n * 16;
;                         f32x4 v = xv[m][bj][n] + acc[ai][bj][m][n] * scl; *(f32x4*)(x + off) = v;
;                         u32x2 w; w.x = cvt_pk_bf16(v[0], v[1]); w.y = cvt_pk_bf16(v[2], v[3]); *(u32x2*)(xb + off) = w;
;                         q += (v[0] * v[0] + v[1] * v[1]) + (v[2] * v[2] + v[3] * v[3]); }
;                 q += bperm(q, (fr + 16 * fq) ^ 16); q += bperm(q, (fr + 16 * fq) ^ 32);
;                 if (fq == 0) P[(ai * HALF + wr * 64 + m * 16 + fr) * 4 + wc] = q; }
.LBB0_411:
	v_readlane_b32 s3, v255, 0
	s_lshl_b32 s2, s20, 5
	s_lshl_b32 s4, s3, 8
	s_lshl_b32 s3, s96, 8
	v_bfe_u32 v193, v192, 4, 2
	s_add_i32 s30, s30, s4
	s_or_b32 s2, s2, s3
	v_or_b32_e32 v182, s30, v136
	v_lshl_or_b32 v180, v193, 2, s2
	v_ashrrev_i32_e32 v181, 31, v180
	v_ashrrev_i32_e32 v183, 31, v182
	v_lshl_add_u64 v[184:185], v[180:181], 2, s[0:1]
	v_lshlrev_b64 v[130:131], 12, v[182:183]
	v_or_b32_e32 v190, 16, v182
	v_mov_b32_e32 v178, 0.5
	v_lshl_add_u64 v[130:131], v[184:185], 0, v[130:131]
	v_ashrrev_i32_e32 v191, 31, v190
	s_barrier
	global_load_dwordx4 v[210:213], v[130:131], off
	global_load_dwordx4 v[214:217], v[130:131], off offset:64
	global_load_dwordx4 v[218:221], v[130:131], off offset:512
	global_load_dwordx4 v[242:245], v[130:131], off offset:576
	v_lshlrev_b64 v[130:131], 12, v[190:191]
	v_or_b32_e32 v188, 32, v182
	v_lshl_add_u64 v[130:131], v[184:185], 0, v[130:131]
	v_ashrrev_i32_e32 v189, 31, v188
	global_load_dwordx4 v[174:177], v[130:131], off
	global_load_dwordx4 v[170:173], v[130:131], off offset:64
	global_load_dwordx4 v[166:169], v[130:131], off offset:512
	global_load_dwordx4 v[162:165], v[130:131], off offset:576
	v_lshlrev_b64 v[130:131], 12, v[188:189]
	v_or_b32_e32 v186, 48, v182
	v_lshl_add_u64 v[130:131], v[184:185], 0, v[130:131]
	v_ashrrev_i32_e32 v187, 31, v186
	global_load_dwordx4 v[158:161], v[130:131], off
	global_load_dwordx4 v[154:157], v[130:131], off offset:64
	global_load_dwordx4 v[150:153], v[130:131], off offset:512
	global_load_dwordx4 v[146:149], v[130:131], off offset:576
	v_lshlrev_b64 v[130:131], 12, v[186:187]
	v_lshl_add_u64 v[130:131], v[184:185], 0, v[130:131]
	global_load_dwordx4 v[142:145], v[130:131], off
	global_load_dwordx4 v[138:141], v[130:131], off offset:64
	global_load_dwordx4 v[134:137], v[130:131], off offset:512
	s_nop 0
	global_load_dwordx4 v[130:133], v[130:131], off offset:576
	v_and_b32_e32 v64, 63, v192
	s_lshl_b32 s2, s20, 2
	v_lshlrev_b32_e32 v192, 6, v193
	s_add_i32 s2, s2, 0
	v_bitop3_b32 v193, v192, 64, v194 bitop3:0x36
	v_bitop3_b32 v192, v192, s93, v194 bitop3:0x36
	v_cmp_gt_u32_e32 vcc, 16, v64
	v_lshlrev_b64 v[194:195], 10, v[182:183]
	v_lshl_add_u64 v[194:195], v[194:195], 0, v[180:181]
	s_waitcnt vmcnt(0)
	v_pk_fma_f32 v[128:129], v[128:129], v[178:179], v[212:213] op_sel_hi:[1,0,1]
	v_pk_fma_f32 v[126:127], v[126:127], v[178:179], v[210:211] op_sel_hi:[1,0,1]
	v_lshl_add_u64 v[210:211], v[194:195], 2, s[76:77]
	global_store_dwordx4 v[210:211], v[126:129], off sc1
	v_cvt_pk_bf16_f32 v212, v126, v127
	v_lshlrev_b64 v[194:195], 1, v[194:195]
	v_lshl_add_u64 v[222:223], s[26:27], 0, v[194:195]
	v_mul_f32_e32 v127, v127, v127
	v_fmac_f32_e32 v127, v126, v126
	v_mul_f32_e32 v126, v129, v129
	v_fmac_f32_e32 v126, v128, v128
	v_pk_fma_f32 v[124:125], v[124:125], v[178:179], v[216:217] op_sel_hi:[1,0,1]
	v_pk_fma_f32 v[122:123], v[122:123], v[178:179], v[214:215] op_sel_hi:[1,0,1]
	v_cvt_pk_bf16_f32 v213, v128, v129
	global_store_dwordx2 v[222:223], v[212:213], off
	v_add_f32_e32 v183, v127, v126
	global_store_dwordx4 v[210:211], v[122:125], off offset:64 sc1
	v_cvt_pk_bf16_f32 v126, v122, v123
	v_or_b32_e32 v128, 32, v194
	v_mov_b32_e32 v129, v195
	v_mul_f32_e32 v123, v123, v123
	v_fmac_f32_e32 v123, v122, v122
	v_mul_f32_e32 v122, v125, v125
	v_fmac_f32_e32 v122, v124, v124
	v_lshl_add_u64 v[128:129], s[26:27], 0, v[128:129]
	v_add_f32_e32 v122, v123, v122
	v_pk_fma_f32 v[120:121], v[120:121], v[178:179], v[220:221] op_sel_hi:[1,0,1]
	v_pk_fma_f32 v[118:119], v[118:119], v[178:179], v[218:219] op_sel_hi:[1,0,1]
	v_cvt_pk_bf16_f32 v127, v124, v125
	global_store_dwordx2 v[128:129], v[126:127], off
	v_add_f32_e32 v126, v183, v122
	global_store_dwordx4 v[210:211], v[118:121], off offset:512 sc1
	v_cvt_pk_bf16_f32 v122, v118, v119
	v_pk_fma_f32 v[116:117], v[116:117], v[178:179], v[244:245] op_sel_hi:[1,0,1]
	v_pk_fma_f32 v[114:115], v[114:115], v[178:179], v[242:243] op_sel_hi:[1,0,1]
	v_mul_f32_e32 v119, v119, v119
	v_fmac_f32_e32 v119, v118, v118
	v_mul_f32_e32 v118, v121, v121
	v_fmac_f32_e32 v118, v120, v120
	v_cvt_pk_bf16_f32 v123, v120, v121
	v_add_f32_e32 v118, v119, v118
	v_mul_f32_e32 v119, v115, v115
	v_mul_f32_e32 v120, v117, v117
	v_fmac_f32_e32 v119, v114, v114
	v_fmac_f32_e32 v120, v116, v116
	v_add_f32_e32 v118, v118, v126
	v_add_f32_e32 v119, v119, v120
	v_add_f32_e32 v120, v119, v118
	ds_bpermute_b32 v121, v193, v120
	v_or_b32_e32 v124, 0x100, v194
	v_mov_b32_e32 v125, v195
	v_lshl_add_u64 v[124:125], s[26:27], 0, v[124:125]
	global_store_dwordx2 v[124:125], v[122:123], off
	global_store_dwordx4 v[210:211], v[114:117], off offset:576 sc1
	v_cvt_pk_bf16_f32 v118, v114, v115
	v_or_b32_e32 v194, 0x120, v194
	v_cvt_pk_bf16_f32 v119, v116, v117
	v_lshl_add_u32 v122, v179, 4, s2
	s_waitcnt lgkmcnt(0)
	v_add_f32_e32 v114, v120, v121
	ds_bpermute_b32 v115, v192, v114
	v_lshl_add_u64 v[116:117], s[26:27], 0, v[194:195]
	global_store_dwordx2 v[116:117], v[118:119], off
	s_and_saveexec_b64 s[2:3], vcc
	s_cbranch_execz .LBB0_413
	s_waitcnt lgkmcnt(0)
	v_add_f32_e32 v114, v114, v115
	ds_write_b32 v122, v114
; __device__ __forceinline__ unsigned cvt_pk_bf16(float lo, float hi) { unsigned r; asm volatile("v_cvt_pk_bf16_f32 %0, %1, %2" : "=v"(r) : "v"(lo), "v"(hi)); return r; }
; __device__ __forceinline__ float bperm(float v, int srclane) { return __int_as_float(__builtin_amdgcn_ds_bpermute(srclane << 2, __float_as_int(v))); }
; __device__ __forceinline__ float bperm(float v, int srclane) { return __int_as_float(__builtin_amdgcn_ds_bpermute(srclane << 2, __float_as_int(v))); }
;     __device__ __forceinline__ void fused(f32x4 (&acc)[2][2][4][2], const Unit& u, int wr, int wc, int fr, int fq, PG8_LAS unsigned char* lds, int wid, int lane) const {
;     ...
;             for (int m = 0; m < 4; ++m) { const int row = row0 + ai * HALF + m * 16; float q = 0.f;
; #pragma unroll
;                 for (int bj = 0; bj < 2; ++bj)
; #pragma unroll
;                     for (int n = 0; n < 2; ++n) { const size_t off = (size_t)row * 1024 + col0 + bj * HALF + n * 16;
;                         f32x4 v = xv[m][bj][n] + acc[ai][bj][m][n] * scl; *(f32x4*)(x + off) = v;
;                         u32x2 w; w.x = cvt_pk_bf16(v[0], v[1]); w.y = cvt_pk_bf16(v[2], v[3]); *(u32x2*)(xb + off) = w;
;                         q += (v[0] * v[0] + v[1] * v[1]) + (v[2] * v[2] + v[3] * v[3]); }
;                 q += bperm(q, (fr + 16 * fq) ^ 16); q += bperm(q, (fr + 16 * fq) ^ 32);
;                 if (fq == 0) P[(ai * HALF + wr * 64 + m * 16 + fr) * 4 + wc] = q; }
.LBB0_413:
	s_or_b64 exec, exec, s[2:3]
	s_waitcnt lgkmcnt(0)
	v_lshlrev_b64 v[114:115], 10, v[190:191]
	v_mov_b32_e32 v179, v178
	v_lshl_add_u64 v[116:117], v[114:115], 0, v[180:181]
	v_mov_b32_e32 v114, v178
	v_mov_b32_e32 v115, v178
	v_pk_fma_f32 v[112:113], v[112:113], v[114:115], v[176:177]
	v_pk_fma_f32 v[110:111], v[110:111], v[178:179], v[174:175]
	v_lshl_add_u64 v[118:119], v[116:117], 2, s[76:77]
	global_store_dwordx4 v[118:119], v[110:113], off sc1
	v_cvt_pk_bf16_f32 v120, v110, v111
	v_lshlrev_b64 v[116:117], 1, v[116:117]
	v_lshl_add_u64 v[124:125], s[26:27], 0, v[116:117]
	v_mul_f32_e32 v111, v111, v111
	v_fmac_f32_e32 v111, v110, v110
	v_mul_f32_e32 v110, v113, v113
	v_fmac_f32_e32 v110, v112, v112
	v_pk_fma_f32 v[108:109], v[108:109], v[114:115], v[172:173]
	v_pk_fma_f32 v[106:107], v[106:107], v[178:179], v[170:171]
	v_cvt_pk_bf16_f32 v121, v112, v113
	global_store_dwordx2 v[124:125], v[120:121], off
	v_add_f32_e32 v120, v111, v110
	global_store_dwordx4 v[118:119], v[106:109], off offset:64 sc1
	v_cvt_pk_bf16_f32 v110, v106, v107
	v_or_b32_e32 v112, 32, v116
	v_mov_b32_e32 v113, v117
	v_mul_f32_e32 v107, v107, v107
	v_fmac_f32_e32 v107, v106, v106
	v_mul_f32_e32 v106, v109, v109
	v_fmac_f32_e32 v106, v108, v108
	v_lshl_add_u64 v[112:113], s[26:27], 0, v[112:113]
	v_add_f32_e32 v106, v107, v106
	v_pk_fma_f32 v[104:105], v[104:105], v[114:115], v[168:169]
	v_pk_fma_f32 v[102:103], v[102:103], v[178:179], v[166:167]
	v_cvt_pk_bf16_f32 v111, v108, v109
	global_store_dwordx2 v[112:113], v[110:111], off
	v_add_f32_e32 v110, v120, v106
	global_store_dwordx4 v[118:119], v[102:105], off offset:512 sc1
	v_cvt_pk_bf16_f32 v106, v102, v103
	v_pk_fma_f32 v[100:101], v[100:101], v[114:115], v[164:165]
	v_pk_fma_f32 v[98:99], v[98:99], v[178:179], v[162:163]
	v_mul_f32_e32 v103, v103, v103
	v_fmac_f32_e32 v103, v102, v102
	v_mul_f32_e32 v102, v105, v105
	v_fmac_f32_e32 v102, v104, v104
	v_cvt_pk_bf16_f32 v107, v104, v105
	v_add_f32_e32 v102, v103, v102
	v_mul_f32_e32 v103, v99, v99
	v_mul_f32_e32 v104, v101, v101
	v_fmac_f32_e32 v103, v98, v98
	v_fmac_f32_e32 v104, v100, v100
	v_add_f32_e32 v102, v110, v102
	v_add_f32_e32 v103, v103, v104
	v_add_f32_e32 v104, v102, v103
	ds_bpermute_b32 v105, v193, v104
	v_or_b32_e32 v108, 0x100, v116
	v_mov_b32_e32 v109, v117
	v_lshl_add_u64 v[102:103], s[26:27], 0, v[108:109]
	global_store_dwordx2 v[102:103], v[106:107], off
	global_store_dwordx4 v[118:119], v[98:101], off offset:576 sc1
	v_cvt_pk_bf16_f32 v102, v98, v99
	v_or_b32_e32 v116, 0x120, v116
	v_cvt_pk_bf16_f32 v103, v100, v101
	s_waitcnt lgkmcnt(0)
	v_add_f32_e32 v98, v104, v105
	ds_bpermute_b32 v99, v192, v98
	v_lshl_add_u64 v[100:101], s[26:27], 0, v[116:117]
	global_store_dwordx2 v[100:101], v[102:103], off
	s_and_saveexec_b64 s[2:3], vcc
	s_cbranch_execz .LBB0_415
	s_waitcnt lgkmcnt(0)
	v_add_f32_e32 v98, v98, v99
	ds_write_b32 v122, v98 offset:256
.LBB0_415:
	s_or_b64 exec, exec, s[2:3]
	s_waitcnt lgkmcnt(0)
	v_lshlrev_b64 v[98:99], 10, v[188:189]
	v_lshl_add_u64 v[98:99], v[98:99], 0, v[180:181]
	v_pk_fma_f32 v[96:97], v[96:97], v[114:115], v[160:161]
	v_pk_fma_f32 v[94:95], v[94:95], v[178:179], v[158:159]
	v_lshl_add_u64 v[100:101], v[98:99], 2, s[76:77]
	global_store_dwordx4 v[100:101], v[94:97], off sc1
	v_cvt_pk_bf16_f32 v102, v94, v95
	v_lshlrev_b64 v[98:99], 1, v[98:99]
	v_lshl_add_u64 v[104:105], s[26:27], 0, v[98:99]
	v_mul_f32_e32 v95, v95, v95
	v_fmac_f32_e32 v95, v94, v94
	v_mul_f32_e32 v94, v97, v97
	v_fmac_f32_e32 v94, v96, v96
	v_pk_fma_f32 v[92:93], v[92:93], v[114:115], v[156:157]
	v_pk_fma_f32 v[90:91], v[90:91], v[178:179], v[154:155]
	v_cvt_pk_bf16_f32 v103, v96, v97
	global_store_dwordx2 v[104:105], v[102:103], off
	v_add_f32_e32 v102, v95, v94
	global_store_dwordx4 v[100:101], v[90:93], off offset:64 sc1
	v_cvt_pk_bf16_f32 v94, v90, v91
	v_or_b32_e32 v96, 32, v98
	v_mov_b32_e32 v97, v99
	v_mul_f32_e32 v91, v91, v91
	v_fmac_f32_e32 v91, v90, v90
	v_mul_f32_e32 v90, v93, v93
	v_fmac_f32_e32 v90, v92, v92
	v_lshl_add_u64 v[96:97], s[26:27], 0, v[96:97]
	v_add_f32_e32 v90, v91, v90
	v_pk_fma_f32 v[88:89], v[88:89], v[114:115], v[152:153]
	v_pk_fma_f32 v[86:87], v[86:87], v[178:179], v[150:151]
	v_cvt_pk_bf16_f32 v95, v92, v93
	global_store_dwordx2 v[96:97], v[94:95], off
	v_add_f32_e32 v94, v102, v90
	global_store_dwordx4 v[100:101], v[86:89], off offset:512 sc1
	v_cvt_pk_bf16_f32 v90, v86, v87
	v_pk_fma_f32 v[84:85], v[84:85], v[114:115], v[148:149]
	v_pk_fma_f32 v[82:83], v[82:83], v[178:179], v[146:147]
	v_mul_f32_e32 v87, v87, v87
	v_fmac_f32_e32 v87, v86, v86
	v_mul_f32_e32 v86, v89, v89
	v_fmac_f32_e32 v86, v88, v88
	v_cvt_pk_bf16_f32 v91, v88, v89
	v_add_f32_e32 v86, v87, v86
	v_mul_f32_e32 v87, v83, v83
	v_mul_f32_e32 v88, v85, v85
	v_fmac_f32_e32 v87, v82, v82
	v_fmac_f32_e32 v88, v84, v84
	v_add_f32_e32 v86, v94, v86
	v_add_f32_e32 v87, v87, v88
	v_add_f32_e32 v88, v86, v87
	ds_bpermute_b32 v89, v193, v88
	v_or_b32_e32 v92, 0x100, v98
	v_mov_b32_e32 v93, v99
	v_lshl_add_u64 v[86:87], s[26:27], 0, v[92:93]
	global_store_dwordx2 v[86:87], v[90:91], off
	global_store_dwordx4 v[100:101], v[82:85], off offset:576 sc1
	v_cvt_pk_bf16_f32 v86, v82, v83
	v_or_b32_e32 v98, 0x120, v98
	v_cvt_pk_bf16_f32 v87, v84, v85
	s_waitcnt lgkmcnt(0)
	v_add_f32_e32 v82, v88, v89
	ds_bpermute_b32 v83, v192, v82
	v_lshl_add_u64 v[84:85], s[26:27], 0, v[98:99]
	global_store_dwordx2 v[84:85], v[86:87], off
	s_and_saveexec_b64 s[2:3], vcc
	s_cbranch_execz .LBB0_417
	s_waitcnt lgkmcnt(0)
	v_add_f32_e32 v82, v82, v83
	ds_write_b32 v122, v82 offset:512
; __device__ __forceinline__ unsigned cvt_pk_bf16(float lo, float hi) { unsigned r; asm volatile("v_cvt_pk_bf16_f32 %0, %1, %2" : "=v"(r) : "v"(lo), "v"(hi)); return r; }
; __device__ __forceinline__ float bperm(float v, int srclane) { return __int_as_float(__builtin_amdgcn_ds_bpermute(srclane << 2, __float_as_int(v))); }
; __device__ __forceinline__ float bperm(float v, int srclane) { return __int_as_float(__builtin_amdgcn_ds_bpermute(srclane << 2, __float_as_int(v))); }
;     __device__ __forceinline__ void fused(f32x4 (&acc)[2][2][4][2], const Unit& u, int wr, int wc, int fr, int fq, PG8_LAS unsigned char* lds, int wid, int lane) const {
;     ...
;                     for (int n = 0; n < 2; ++n) xv[m][bj][n] = *(const f32x4*)(xin + (size_t)(row0 + ai * HALF + m * 16) * 1024 + col0 + bj * HALF + n * 16);
;             __builtin_amdgcn_sched_barrier(0);
; #pragma unroll
;             for (int m = 0; m < 4; ++m) { const int row = row0 + ai * HALF + m * 16; float q = 0.f;
; #pragma unroll
;                 for (int bj = 0; bj < 2; ++bj)
; #pragma unroll
;                     for (int n = 0; n < 2; ++n) { const size_t off = (size_t)row * 1024 + col0 + bj * HALF + n * 16;
;                         f32x4 v = xv[m][bj][n] + acc[ai][bj][m][n] * scl; *(f32x4*)(x + off) = v;
;                         u32x2 w; w.x = cvt_pk_bf16(v[0], v[1]); w.y = cvt_pk_bf16(v[2], v[3]); *(u32x2*)(xb + off) = w;
;                         q += (v[0] * v[0] + v[1] * v[1]) + (v[2] * v[2] + v[3] * v[3]); }
;                 q += bperm(q, (fr + 16 * fq) ^ 16); q += bperm(q, (fr + 16 * fq) ^ 32);
;                 if (fq == 0) P[(ai * HALF + wr * 64 + m * 16 + fr) * 4 + wc] = q; }
.LBB0_417:
	s_or_b64 exec, exec, s[2:3]
	s_waitcnt lgkmcnt(0)
	v_lshlrev_b64 v[82:83], 10, v[186:187]
	v_lshl_add_u64 v[82:83], v[82:83], 0, v[180:181]
	v_mov_b32_e32 v118, v178
	v_mov_b32_e32 v119, v178
	v_pk_fma_f32 v[80:81], v[80:81], v[118:119], v[144:145]
	v_pk_fma_f32 v[78:79], v[78:79], v[178:179], v[142:143]
	v_lshl_add_u64 v[84:85], v[82:83], 2, s[76:77]
	global_store_dwordx4 v[84:85], v[78:81], off sc1
	v_cvt_pk_bf16_f32 v86, v78, v79
	v_lshlrev_b64 v[82:83], 1, v[82:83]
	v_lshl_add_u64 v[88:89], s[26:27], 0, v[82:83]
	v_mul_f32_e32 v79, v79, v79
	v_fmac_f32_e32 v79, v78, v78
	v_mul_f32_e32 v78, v81, v81
	v_fmac_f32_e32 v78, v80, v80
	v_pk_fma_f32 v[76:77], v[76:77], v[118:119], v[140:141]
	v_pk_fma_f32 v[74:75], v[74:75], v[178:179], v[138:139]
	v_cvt_pk_bf16_f32 v87, v80, v81
	global_store_dwordx2 v[88:89], v[86:87], off
	v_add_f32_e32 v86, v79, v78
	global_store_dwordx4 v[84:85], v[74:77], off offset:64 sc1
	v_cvt_pk_bf16_f32 v78, v74, v75
	v_or_b32_e32 v80, 32, v82
	v_mov_b32_e32 v81, v83
	v_mul_f32_e32 v75, v75, v75
	v_fmac_f32_e32 v75, v74, v74
	v_mul_f32_e32 v74, v77, v77
	v_fmac_f32_e32 v74, v76, v76
	v_lshl_add_u64 v[80:81], s[26:27], 0, v[80:81]
	v_add_f32_e32 v74, v75, v74
	v_pk_fma_f32 v[72:73], v[72:73], v[118:119], v[136:137]
	v_pk_fma_f32 v[70:71], v[70:71], v[178:179], v[134:135]
	v_cvt_pk_bf16_f32 v79, v76, v77
	global_store_dwordx2 v[80:81], v[78:79], off
	v_add_f32_e32 v78, v86, v74
	global_store_dwordx4 v[84:85], v[70:73], off offset:512 sc1
	v_cvt_pk_bf16_f32 v74, v70, v71
	v_pk_fma_f32 v[68:69], v[68:69], v[118:119], v[132:133]
	v_pk_fma_f32 v[66:67], v[66:67], v[178:179], v[130:131]
	v_mul_f32_e32 v71, v71, v71
	v_fmac_f32_e32 v71, v70, v70
	v_mul_f32_e32 v70, v73, v73
	v_fmac_f32_e32 v70, v72, v72
	v_cvt_pk_bf16_f32 v75, v72, v73
	v_add_f32_e32 v70, v71, v70
	v_mul_f32_e32 v71, v67, v67
	v_mul_f32_e32 v72, v69, v69
	v_fmac_f32_e32 v71, v66, v66
	v_fmac_f32_e32 v72, v68, v68
	v_add_f32_e32 v70, v78, v70
	v_add_f32_e32 v71, v71, v72
	v_add_f32_e32 v72, v70, v71
	ds_bpermute_b32 v73, v193, v72
	v_or_b32_e32 v76, 0x100, v82
	v_mov_b32_e32 v77, v83
	v_lshl_add_u64 v[70:71], s[26:27], 0, v[76:77]
	global_store_dwordx2 v[70:71], v[74:75], off
	global_store_dwordx4 v[84:85], v[66:69], off offset:576 sc1
	v_cvt_pk_bf16_f32 v70, v66, v67
	v_or_b32_e32 v82, 0x120, v82
	v_cvt_pk_bf16_f32 v71, v68, v69
	s_waitcnt lgkmcnt(0)
	v_add_f32_e32 v66, v72, v73
	ds_bpermute_b32 v67, v192, v66
	v_lshl_add_u64 v[68:69], s[26:27], 0, v[82:83]
	global_store_dwordx2 v[68:69], v[70:71], off
	s_and_saveexec_b64 s[2:3], vcc
	s_cbranch_execz .LBB0_419
	s_waitcnt lgkmcnt(0)
	v_add_f32_e32 v66, v66, v67
	ds_write_b32 v122, v66 offset:768
.LBB0_419:
	s_or_b64 exec, exec, s[2:3]
	v_add_u32_e32 v140, 0x80, v182
	v_ashrrev_i32_e32 v141, 31, v140
	s_waitcnt lgkmcnt(0)
	v_lshlrev_b64 v[66:67], 12, v[140:141]
	v_add_u32_e32 v120, 0x90, v182
	v_lshl_add_u64 v[66:67], v[184:185], 0, v[66:67]
	v_ashrrev_i32_e32 v121, 31, v120
	global_load_dwordx4 v[124:127], v[66:67], off
	global_load_dwordx4 v[128:131], v[66:67], off offset:64
	global_load_dwordx4 v[132:135], v[66:67], off offset:512
	global_load_dwordx4 v[136:139], v[66:67], off offset:576
	v_lshlrev_b64 v[66:67], 12, v[120:121]
	v_add_u32_e32 v116, 0xa0, v182
	v_lshl_add_u64 v[66:67], v[184:185], 0, v[66:67]
	v_ashrrev_i32_e32 v117, 31, v116
	global_load_dwordx4 v[110:113], v[66:67], off
	global_load_dwordx4 v[106:109], v[66:67], off offset:64
	global_load_dwordx4 v[102:105], v[66:67], off offset:512
	global_load_dwordx4 v[98:101], v[66:67], off offset:576
	v_lshlrev_b64 v[66:67], 12, v[116:117]
	v_add_u32_e32 v114, 0xb0, v182
	v_lshl_add_u64 v[66:67], v[184:185], 0, v[66:67]
	v_ashrrev_i32_e32 v115, 31, v114
	global_load_dwordx4 v[94:97], v[66:67], off
	global_load_dwordx4 v[90:93], v[66:67], off offset:64
	global_load_dwordx4 v[86:89], v[66:67], off offset:512
	global_load_dwordx4 v[82:85], v[66:67], off offset:576
	v_lshlrev_b64 v[66:67], 12, v[114:115]
	v_lshl_add_u64 v[66:67], v[184:185], 0, v[66:67]
	global_load_dwordx4 v[78:81], v[66:67], off
	global_load_dwordx4 v[74:77], v[66:67], off offset:64
	global_load_dwordx4 v[70:73], v[66:67], off offset:512
	s_nop 0
	global_load_dwordx4 v[66:69], v[66:67], off offset:576
	v_lshlrev_b64 v[140:141], 10, v[140:141]
	v_lshl_add_u64 v[140:141], v[140:141], 0, v[180:181]
	s_waitcnt vmcnt(15)
	v_pk_fma_f32 v[62:63], v[62:63], v[118:119], v[126:127]
	v_pk_fma_f32 v[60:61], v[60:61], v[178:179], v[124:125]
	v_lshl_add_u64 v[124:125], v[140:141], 2, s[76:77]
	global_store_dwordx4 v[124:125], v[60:63], off sc1
	v_cvt_pk_bf16_f32 v126, v60, v61
	v_lshlrev_b64 v[140:141], 1, v[140:141]
	v_lshl_add_u64 v[142:143], s[26:27], 0, v[140:141]
	v_mul_f32_e32 v61, v61, v61
	v_fmac_f32_e32 v61, v60, v60
	v_mul_f32_e32 v60, v63, v63
	v_fmac_f32_e32 v60, v62, v62
	s_waitcnt vmcnt(15)
	v_pk_fma_f32 v[58:59], v[58:59], v[118:119], v[130:131]
	v_pk_fma_f32 v[56:57], v[56:57], v[178:179], v[128:129]
	v_cvt_pk_bf16_f32 v127, v62, v63
	global_store_dwordx2 v[142:143], v[126:127], off
	v_add_f32_e32 v123, v61, v60
	global_store_dwordx4 v[124:125], v[56:59], off offset:64 sc1
	v_cvt_pk_bf16_f32 v60, v56, v57
	v_or_b32_e32 v62, 32, v140
	v_mov_b32_e32 v63, v141
	v_mul_f32_e32 v57, v57, v57
	v_fmac_f32_e32 v57, v56, v56
	v_mul_f32_e32 v56, v59, v59
	v_fmac_f32_e32 v56, v58, v58
	v_lshl_add_u64 v[62:63], s[26:27], 0, v[62:63]
	v_add_f32_e32 v56, v57, v56
	s_waitcnt vmcnt(16)
	v_pk_fma_f32 v[54:55], v[54:55], v[118:119], v[134:135]
	v_pk_fma_f32 v[52:53], v[52:53], v[178:179], v[132:133]
	v_cvt_pk_bf16_f32 v61, v58, v59
	global_store_dwordx2 v[62:63], v[60:61], off
	v_add_f32_e32 v60, v123, v56
	global_store_dwordx4 v[124:125], v[52:55], off offset:512 sc1
	v_cvt_pk_bf16_f32 v56, v52, v53
	s_waitcnt vmcnt(17)
	v_pk_fma_f32 v[50:51], v[50:51], v[118:119], v[138:139]
	v_pk_fma_f32 v[48:49], v[48:49], v[178:179], v[136:137]
	v_mul_f32_e32 v53, v53, v53
	v_fmac_f32_e32 v53, v52, v52
	v_mul_f32_e32 v52, v55, v55
	v_fmac_f32_e32 v52, v54, v54
	v_cvt_pk_bf16_f32 v57, v54, v55
	v_add_f32_e32 v52, v53, v52
	v_mul_f32_e32 v53, v49, v49
	v_mul_f32_e32 v54, v51, v51
	v_fmac_f32_e32 v53, v48, v48
	v_fmac_f32_e32 v54, v50, v50
	v_add_f32_e32 v52, v60, v52
	v_add_f32_e32 v53, v53, v54
	v_add_f32_e32 v54, v52, v53
	ds_bpermute_b32 v55, v193, v54
	v_or_b32_e32 v58, 0x100, v140
	v_mov_b32_e32 v59, v141
	v_lshl_add_u64 v[52:53], s[26:27], 0, v[58:59]
	global_store_dwordx2 v[52:53], v[56:57], off
	global_store_dwordx4 v[124:125], v[48:51], off offset:576 sc1
	v_cvt_pk_bf16_f32 v52, v48, v49
	v_or_b32_e32 v140, 0x120, v140
	v_cvt_pk_bf16_f32 v53, v50, v51
	s_waitcnt lgkmcnt(0)
	v_add_f32_e32 v48, v54, v55
	ds_bpermute_b32 v49, v192, v48
	v_lshl_add_u64 v[50:51], s[26:27], 0, v[140:141]
	global_store_dwordx2 v[50:51], v[52:53], off
	s_and_saveexec_b64 s[2:3], vcc
	s_cbranch_execz .LBB0_421
	s_waitcnt lgkmcnt(0)
	v_add_f32_e32 v48, v48, v49
	ds_write_b32 v122, v48 offset:2048
; __device__ __forceinline__ unsigned cvt_pk_bf16(float lo, float hi) { unsigned r; asm volatile("v_cvt_pk_bf16_f32 %0, %1, %2" : "=v"(r) : "v"(lo), "v"(hi)); return r; }
; __device__ __forceinline__ float bperm(float v, int srclane) { return __int_as_float(__builtin_amdgcn_ds_bpermute(srclane << 2, __float_as_int(v))); }
; __device__ __forceinline__ float bperm(float v, int srclane) { return __int_as_float(__builtin_amdgcn_ds_bpermute(srclane << 2, __float_as_int(v))); }
;     __device__ __forceinline__ void fused(f32x4 (&acc)[2][2][4][2], const Unit& u, int wr, int wc, int fr, int fq, PG8_LAS unsigned char* lds, int wid, int lane) const {
;     ...
;             for (int m = 0; m < 4; ++m) { const int row = row0 + ai * HALF + m * 16; float q = 0.f;
; #pragma unroll
;                 for (int bj = 0; bj < 2; ++bj)
; #pragma unroll
;                     for (int n = 0; n < 2; ++n) { const size_t off = (size_t)row * 1024 + col0 + bj * HALF + n * 16;
;                         f32x4 v = xv[m][bj][n] + acc[ai][bj][m][n] * scl; *(f32x4*)(x + off) = v;
;                         u32x2 w; w.x = cvt_pk_bf16(v[0], v[1]); w.y = cvt_pk_bf16(v[2], v[3]); *(u32x2*)(xb + off) = w;
;                         q += (v[0] * v[0] + v[1] * v[1]) + (v[2] * v[2] + v[3] * v[3]); }
;                 q += bperm(q, (fr + 16 * fq) ^ 16); q += bperm(q, (fr + 16 * fq) ^ 32);
;                 if (fq == 0) P[(ai * HALF + wr * 64 + m * 16 + fr) * 4 + wc] = q; }
.LBB0_421:
	s_or_b64 exec, exec, s[2:3]
	s_waitcnt lgkmcnt(0)
	v_lshlrev_b64 v[48:49], 10, v[120:121]
	v_lshl_add_u64 v[50:51], v[48:49], 0, v[180:181]
	v_mov_b32_e32 v48, v178
	v_mov_b32_e32 v49, v178
	s_waitcnt vmcnt(19)
	v_pk_fma_f32 v[46:47], v[46:47], v[48:49], v[112:113]
	v_pk_fma_f32 v[44:45], v[44:45], v[178:179], v[110:111]
	v_lshl_add_u64 v[52:53], v[50:51], 2, s[76:77]
	global_store_dwordx4 v[52:53], v[44:47], off sc1
	v_cvt_pk_bf16_f32 v54, v44, v45
	v_lshlrev_b64 v[50:51], 1, v[50:51]
	v_lshl_add_u64 v[56:57], s[26:27], 0, v[50:51]
	v_mul_f32_e32 v45, v45, v45
	v_fmac_f32_e32 v45, v44, v44
	v_mul_f32_e32 v44, v47, v47
	v_fmac_f32_e32 v44, v46, v46
	s_waitcnt vmcnt(19)
	v_pk_fma_f32 v[42:43], v[42:43], v[48:49], v[108:109]
	v_pk_fma_f32 v[40:41], v[40:41], v[178:179], v[106:107]
	v_cvt_pk_bf16_f32 v55, v46, v47
	global_store_dwordx2 v[56:57], v[54:55], off
	v_add_f32_e32 v54, v45, v44
	global_store_dwordx4 v[52:53], v[40:43], off offset:64 sc1
	v_cvt_pk_bf16_f32 v44, v40, v41
	v_or_b32_e32 v46, 32, v50
	v_mov_b32_e32 v47, v51
	v_mul_f32_e32 v41, v41, v41
	v_fmac_f32_e32 v41, v40, v40
	v_mul_f32_e32 v40, v43, v43
	v_fmac_f32_e32 v40, v42, v42
	v_lshl_add_u64 v[46:47], s[26:27], 0, v[46:47]
	v_add_f32_e32 v40, v41, v40
	s_waitcnt vmcnt(20)
	v_pk_fma_f32 v[38:39], v[38:39], v[48:49], v[104:105]
	v_pk_fma_f32 v[36:37], v[36:37], v[178:179], v[102:103]
	v_cvt_pk_bf16_f32 v45, v42, v43
	global_store_dwordx2 v[46:47], v[44:45], off
	v_add_f32_e32 v44, v54, v40
	global_store_dwordx4 v[52:53], v[36:39], off offset:512 sc1
	v_cvt_pk_bf16_f32 v40, v36, v37
	s_waitcnt vmcnt(21)
	v_pk_fma_f32 v[34:35], v[34:35], v[48:49], v[100:101]
	v_pk_fma_f32 v[32:33], v[32:33], v[178:179], v[98:99]
	v_mul_f32_e32 v37, v37, v37
	v_fmac_f32_e32 v37, v36, v36
	v_mul_f32_e32 v36, v39, v39
	v_fmac_f32_e32 v36, v38, v38
	v_cvt_pk_bf16_f32 v41, v38, v39
	v_add_f32_e32 v36, v37, v36
	v_mul_f32_e32 v37, v33, v33
	v_mul_f32_e32 v38, v35, v35
	v_fmac_f32_e32 v37, v32, v32
	v_fmac_f32_e32 v38, v34, v34
	v_add_f32_e32 v36, v44, v36
	v_add_f32_e32 v37, v37, v38
	v_add_f32_e32 v38, v36, v37
	ds_bpermute_b32 v39, v193, v38
	v_or_b32_e32 v42, 0x100, v50
	v_mov_b32_e32 v43, v51
	v_lshl_add_u64 v[36:37], s[26:27], 0, v[42:43]
	global_store_dwordx2 v[36:37], v[40:41], off
	global_store_dwordx4 v[52:53], v[32:35], off offset:576 sc1
	v_cvt_pk_bf16_f32 v36, v32, v33
	v_or_b32_e32 v50, 0x120, v50
	v_cvt_pk_bf16_f32 v37, v34, v35
	s_waitcnt lgkmcnt(0)
	v_add_f32_e32 v32, v38, v39
	ds_bpermute_b32 v33, v192, v32
	v_lshl_add_u64 v[34:35], s[26:27], 0, v[50:51]
	global_store_dwordx2 v[34:35], v[36:37], off
	s_and_saveexec_b64 s[2:3], vcc
	s_cbranch_execz .LBB0_423
	s_waitcnt lgkmcnt(0)
	v_add_f32_e32 v32, v32, v33
	ds_write_b32 v122, v32 offset:2304
; __device__ __forceinline__ unsigned cvt_pk_bf16(float lo, float hi) { unsigned r; asm volatile("v_cvt_pk_bf16_f32 %0, %1, %2" : "=v"(r) : "v"(lo), "v"(hi)); return r; }
; __device__ __forceinline__ float bperm(float v, int srclane) { return __int_as_float(__builtin_amdgcn_ds_bpermute(srclane << 2, __float_as_int(v))); }
; __device__ __forceinline__ float bperm(float v, int srclane) { return __int_as_float(__builtin_amdgcn_ds_bpermute(srclane << 2, __float_as_int(v))); }
;     __device__ __forceinline__ void fused(f32x4 (&acc)[2][2][4][2], const Unit& u, int wr, int wc, int fr, int fq, PG8_LAS unsigned char* lds, int wid, int lane) const {
;     ...
;             for (int m = 0; m < 4; ++m) { const int row = row0 + ai * HALF + m * 16; float q = 0.f;
; #pragma unroll
;                 for (int bj = 0; bj < 2; ++bj)
; #pragma unroll
;                     for (int n = 0; n < 2; ++n) { const size_t off = (size_t)row * 1024 + col0 + bj * HALF + n * 16;
;                         f32x4 v = xv[m][bj][n] + acc[ai][bj][m][n] * scl; *(f32x4*)(x + off) = v;
;                         u32x2 w; w.x = cvt_pk_bf16(v[0], v[1]); w.y = cvt_pk_bf16(v[2], v[3]); *(u32x2*)(xb + off) = w;
;                         q += (v[0] * v[0] + v[1] * v[1]) + (v[2] * v[2] + v[3] * v[3]); }
;                 q += bperm(q, (fr + 16 * fq) ^ 16); q += bperm(q, (fr + 16 * fq) ^ 32);
;                 if (fq == 0) P[(ai * HALF + wr * 64 + m * 16 + fr) * 4 + wc] = q; }
.LBB0_423:
	s_or_b64 exec, exec, s[2:3]
	s_waitcnt lgkmcnt(0)
	v_lshlrev_b64 v[32:33], 10, v[116:117]
	v_lshl_add_u64 v[32:33], v[32:33], 0, v[180:181]
	s_waitcnt vmcnt(23)
	v_pk_fma_f32 v[30:31], v[30:31], v[48:49], v[96:97]
	v_pk_fma_f32 v[28:29], v[28:29], v[178:179], v[94:95]
	v_lshl_add_u64 v[34:35], v[32:33], 2, s[76:77]
	global_store_dwordx4 v[34:35], v[28:31], off sc1
	v_cvt_pk_bf16_f32 v36, v28, v29
	v_lshlrev_b64 v[32:33], 1, v[32:33]
	v_lshl_add_u64 v[38:39], s[26:27], 0, v[32:33]
	v_mul_f32_e32 v29, v29, v29
	v_fmac_f32_e32 v29, v28, v28
	v_mul_f32_e32 v28, v31, v31
	v_fmac_f32_e32 v28, v30, v30
	s_waitcnt vmcnt(23)
	v_pk_fma_f32 v[26:27], v[26:27], v[48:49], v[92:93]
	v_pk_fma_f32 v[24:25], v[24:25], v[178:179], v[90:91]
	v_cvt_pk_bf16_f32 v37, v30, v31
	global_store_dwordx2 v[38:39], v[36:37], off
	v_add_f32_e32 v36, v29, v28
	global_store_dwordx4 v[34:35], v[24:27], off offset:64 sc1
	v_cvt_pk_bf16_f32 v28, v24, v25
	v_or_b32_e32 v30, 32, v32
	v_mov_b32_e32 v31, v33
	v_mul_f32_e32 v25, v25, v25
	v_fmac_f32_e32 v25, v24, v24
	v_mul_f32_e32 v24, v27, v27
	v_fmac_f32_e32 v24, v26, v26
	v_lshl_add_u64 v[30:31], s[26:27], 0, v[30:31]
	v_add_f32_e32 v24, v25, v24
	s_waitcnt vmcnt(24)
	v_pk_fma_f32 v[22:23], v[22:23], v[48:49], v[88:89]
	v_pk_fma_f32 v[20:21], v[20:21], v[178:179], v[86:87]
	v_cvt_pk_bf16_f32 v29, v26, v27
	global_store_dwordx2 v[30:31], v[28:29], off
	v_add_f32_e32 v28, v36, v24
	global_store_dwordx4 v[34:35], v[20:23], off offset:512 sc1
	v_cvt_pk_bf16_f32 v24, v20, v21
	s_waitcnt vmcnt(25)
	v_pk_fma_f32 v[18:19], v[18:19], v[48:49], v[84:85]
	v_pk_fma_f32 v[16:17], v[16:17], v[178:179], v[82:83]
	v_mul_f32_e32 v21, v21, v21
	v_fmac_f32_e32 v21, v20, v20
	v_mul_f32_e32 v20, v23, v23
	v_fmac_f32_e32 v20, v22, v22
	v_cvt_pk_bf16_f32 v25, v22, v23
	v_add_f32_e32 v20, v21, v20
	v_mul_f32_e32 v21, v17, v17
	v_mul_f32_e32 v22, v19, v19
	v_fmac_f32_e32 v21, v16, v16
	v_fmac_f32_e32 v22, v18, v18
	v_add_f32_e32 v20, v28, v20
	v_add_f32_e32 v21, v21, v22
	v_add_f32_e32 v22, v20, v21
	ds_bpermute_b32 v23, v193, v22
	v_or_b32_e32 v26, 0x100, v32
	v_mov_b32_e32 v27, v33
	v_lshl_add_u64 v[20:21], s[26:27], 0, v[26:27]
	global_store_dwordx2 v[20:21], v[24:25], off
	global_store_dwordx4 v[34:35], v[16:19], off offset:576 sc1
	v_cvt_pk_bf16_f32 v20, v16, v17
	v_or_b32_e32 v32, 0x120, v32
	v_cvt_pk_bf16_f32 v21, v18, v19
	s_waitcnt lgkmcnt(0)
	v_add_f32_e32 v16, v22, v23
	ds_bpermute_b32 v17, v192, v16
	v_lshl_add_u64 v[18:19], s[26:27], 0, v[32:33]
	global_store_dwordx2 v[18:19], v[20:21], off
	s_and_saveexec_b64 s[2:3], vcc
	s_cbranch_execz .LBB0_425
	s_waitcnt lgkmcnt(0)
	v_add_f32_e32 v16, v16, v17
	ds_write_b32 v122, v16 offset:2560
.LBB0_425:
	s_or_b64 exec, exec, s[2:3]
	s_waitcnt lgkmcnt(0)
	v_lshlrev_b64 v[16:17], 10, v[114:115]
	v_lshl_add_u64 v[16:17], v[16:17], 0, v[180:181]
	v_mov_b32_e32 v18, v178
	v_mov_b32_e32 v19, v178
	s_waitcnt vmcnt(27)
	v_pk_fma_f32 v[14:15], v[14:15], v[18:19], v[80:81]
	v_pk_fma_f32 v[12:13], v[12:13], v[178:179], v[78:79]
	v_lshl_add_u64 v[20:21], v[16:17], 2, s[76:77]
	global_store_dwordx4 v[20:21], v[12:15], off sc1
	v_cvt_pk_bf16_f32 v22, v12, v13
	v_lshlrev_b64 v[16:17], 1, v[16:17]
	v_lshl_add_u64 v[24:25], s[26:27], 0, v[16:17]
	v_mul_f32_e32 v13, v13, v13
	v_fmac_f32_e32 v13, v12, v12
	v_mul_f32_e32 v12, v15, v15
	v_fmac_f32_e32 v12, v14, v14
	s_waitcnt vmcnt(27)
	v_pk_fma_f32 v[10:11], v[10:11], v[18:19], v[76:77]
	v_pk_fma_f32 v[8:9], v[8:9], v[178:179], v[74:75]
	v_cvt_pk_bf16_f32 v23, v14, v15
	global_store_dwordx2 v[24:25], v[22:23], off
	v_add_f32_e32 v22, v13, v12
	global_store_dwordx4 v[20:21], v[8:11], off offset:64 sc1
	v_cvt_pk_bf16_f32 v12, v8, v9
	v_or_b32_e32 v14, 32, v16
	v_mov_b32_e32 v15, v17
	v_mul_f32_e32 v9, v9, v9
	v_fmac_f32_e32 v9, v8, v8
	v_mul_f32_e32 v8, v11, v11
	v_fmac_f32_e32 v8, v10, v10
	v_lshl_add_u64 v[14:15], s[26:27], 0, v[14:15]
	v_add_f32_e32 v8, v9, v8
	s_waitcnt vmcnt(28)
	v_pk_fma_f32 v[6:7], v[6:7], v[18:19], v[72:73]
	v_pk_fma_f32 v[4:5], v[4:5], v[178:179], v[70:71]
	v_cvt_pk_bf16_f32 v13, v10, v11
	global_store_dwordx2 v[14:15], v[12:13], off
	v_add_f32_e32 v12, v22, v8
	global_store_dwordx4 v[20:21], v[4:7], off offset:512 sc1
	v_cvt_pk_bf16_f32 v8, v4, v5
	s_waitcnt vmcnt(29)
	v_pk_fma_f32 v[2:3], v[2:3], v[18:19], v[68:69]
	v_pk_fma_f32 v[0:1], v[0:1], v[178:179], v[66:67]
	v_mul_f32_e32 v5, v5, v5
	v_fmac_f32_e32 v5, v4, v4
	v_mul_f32_e32 v4, v7, v7
	v_fmac_f32_e32 v4, v6, v6
	v_cvt_pk_bf16_f32 v9, v6, v7
	v_add_f32_e32 v4, v5, v4
	v_mul_f32_e32 v5, v1, v1
	v_mul_f32_e32 v6, v3, v3
	v_fmac_f32_e32 v5, v0, v0
	v_fmac_f32_e32 v6, v2, v2
	v_add_f32_e32 v4, v12, v4
	v_add_f32_e32 v5, v5, v6
	v_add_f32_e32 v6, v4, v5
	ds_bpermute_b32 v7, v193, v6
	v_or_b32_e32 v10, 0x100, v16
	v_mov_b32_e32 v11, v17
	v_lshl_add_u64 v[4:5], s[26:27], 0, v[10:11]
	global_store_dwordx2 v[4:5], v[8:9], off
	global_store_dwordx4 v[20:21], v[0:3], off offset:576 sc1
	v_cvt_pk_bf16_f32 v4, v0, v1
	v_or_b32_e32 v16, 0x120, v16
	v_cvt_pk_bf16_f32 v5, v2, v3
	s_waitcnt lgkmcnt(0)
	v_add_f32_e32 v0, v6, v7
	ds_bpermute_b32 v1, v192, v0
	v_lshl_add_u64 v[2:3], s[26:27], 0, v[16:17]
	global_store_dwordx2 v[2:3], v[4:5], off
	s_and_saveexec_b64 s[2:3], vcc
	s_cbranch_execz .LBB0_427
	s_waitcnt lgkmcnt(0)
	v_add_f32_e32 v0, v0, v1
	ds_write_b32 v122, v0 offset:2816

; #define PG8_LAS __attribute__((address_space(3)))
; __device__ __forceinline__ unsigned cvt_pk_bf16(float lo, float hi) { unsigned r; asm volatile("v_cvt_pk_bf16_f32 %0, %1, %2" : "=v"(r) : "v"(lo), "v"(hi)); return r; }
; __device__ __forceinline__ float bperm(float v, int srclane) { return __int_as_float(__builtin_amdgcn_ds_bpermute(srclane << 2, __float_as_int(v))); }
; __device__ __forceinline__ float bperm(float v, int srclane) { return __int_as_float(__builtin_amdgcn_ds_bpermute(srclane << 2, __float_as_int(v))); }
;     __device__ __forceinline__ void fused(f32x4 (&acc)[2][2][4][2], const Unit& u, int wr, int wc, int fr, int fq, PG8_LAS unsigned char* lds, int wid, int lane) const {
;         float scl = scale; asm volatile("" : "+v"(scl)); const int row0 = u.pm * BM + wr * 64 + fr, col0 = u.pn * BM + wc * 32 + 4 * fq;
;         PG8_LAS float* P = (PG8_LAS float*)lds;
; #pragma unroll
;         for (int ai = 0; ai < 2; ++ai) { f32x4 xv[4][2][2];
; #pragma unroll
;             for (int m = 0; m < 4; ++m)
; #pragma unroll
;                 for (int bj = 0; bj < 2; ++bj)
; #pragma unroll
;                     for (int n = 0; n < 2; ++n) xv[m][bj][n] = *(const f32x4*)(xin + (size_t)(row0 + ai * HALF + m * 16) * 1024 + col0 + bj * HALF + n * 16);
;             __builtin_amdgcn_sched_barrier(0);
; #pragma unroll
;             for (int m = 0; m < 4; ++m) { const int row = row0 + ai * HALF + m * 16; float q = 0.f;
; #pragma unroll
;                 for (int bj = 0; bj < 2; ++bj)
; #pragma unroll
;                     for (int n = 0; n < 2; ++n) { const size_t off = (size_t)row * 1024 + col0 + bj * HALF + n * 16;
;                         f32x4 v = xv[m][bj][n] + acc[ai][bj][m][n] * scl; *(f32x4*)(x + off) = v;
;                         u32x2 w; w.x = cvt_pk_bf16(v[0], v[1]); w.y = cvt_pk_bf16(v[2], v[3]); *(u32x2*)(xb + off) = w;
;                         q += (v[0] * v[0] + v[1] * v[1]) + (v[2] * v[2] + v[3] * v[3]); }
;                 q += bperm(q, (fr + 16 * fq) ^ 16); q += bperm(q, (fr + 16 * fq) ^ 32);
;                 if (fq == 0) P[(ai * HALF + wr * 64 + m * 16 + fr) * 4 + wc] = q; }
.LBB0_1186:
	s_lshl_b32 s0, s24, 5
	s_lshl_b32 s4, s64, 8
	s_lshl_b32 s1, s62, 8
	v_bfe_u32 v130, v136, 4, 2
	s_add_i32 s30, s30, s4
	s_or_b32 s0, s0, s1
	v_or_b32_e32 v182, s30, v138
	v_lshl_or_b32 v180, v130, 2, s0
	v_ashrrev_i32_e32 v181, 31, v180
	v_lshlrev_b32_e32 v130, 6, v130
	v_ashrrev_i32_e32 v183, 31, v182
	v_or_b32_e32 v210, 16, v182
	v_bitop3_b32 v213, v130, 64, v137 bitop3:0x36
	v_bitop3_b32 v212, v130, s93, v137 bitop3:0x36
	v_lshl_add_u64 v[184:185], v[180:181], 2, s[76:77]
	v_lshlrev_b64 v[130:131], 12, v[182:183]
	v_ashrrev_i32_e32 v211, 31, v210
	v_or_b32_e32 v192, 32, v182
	v_lshl_add_u64 v[222:223], v[184:185], 0, v[130:131]
	v_lshlrev_b64 v[130:131], 12, v[210:211]
	v_ashrrev_i32_e32 v193, 31, v192
	v_or_b32_e32 v188, 48, v182
	v_lshl_add_u64 v[194:195], v[184:185], 0, v[130:131]
	v_lshlrev_b64 v[130:131], 12, v[192:193]
	v_ashrrev_i32_e32 v189, 31, v188
	v_lshl_add_u64 v[190:191], v[184:185], 0, v[130:131]
	v_lshlrev_b64 v[130:131], 12, v[188:189]
	v_mov_b32_e32 v178, 1.0
	v_lshl_add_u64 v[186:187], v[184:185], 0, v[130:131]
	v_and_b32_e32 v64, 63, v136
	s_barrier
	global_load_dwordx4 v[214:217], v[222:223], off
	global_load_dwordx4 v[218:221], v[222:223], off offset:64
	global_load_dwordx4 v[242:245], v[222:223], off offset:512
	global_load_dwordx4 v[246:249], v[222:223], off offset:576
	global_load_dwordx4 v[174:177], v[194:195], off
	global_load_dwordx4 v[170:173], v[194:195], off offset:64
	global_load_dwordx4 v[166:169], v[194:195], off offset:512
	global_load_dwordx4 v[162:165], v[194:195], off offset:576
	global_load_dwordx4 v[158:161], v[190:191], off
	global_load_dwordx4 v[154:157], v[190:191], off offset:64
	global_load_dwordx4 v[150:153], v[190:191], off offset:512
	global_load_dwordx4 v[146:149], v[190:191], off offset:576
	global_load_dwordx4 v[142:145], v[186:187], off
	global_load_dwordx4 v[138:141], v[186:187], off offset:64
	global_load_dwordx4 v[134:137], v[186:187], off offset:512
	global_load_dwordx4 v[130:133], v[186:187], off offset:576
	s_lshl_b32 s0, s24, 2
	s_add_i32 s0, s0, 0
	v_cmp_gt_u32_e32 vcc, 16, v64
	v_lshlrev_b64 v[230:231], 10, v[182:183]
	s_waitcnt vmcnt(0)
	v_pk_fma_f32 v[128:129], v[128:129], v[178:179], v[216:217] op_sel_hi:[1,0,1]
	v_pk_fma_f32 v[126:127], v[126:127], v[178:179], v[214:215] op_sel_hi:[1,0,1]
	v_lshl_add_u64 v[230:231], v[230:231], 0, v[180:181]
	global_store_dwordx4 v[222:223], v[126:129], off sc1
	v_cvt_pk_bf16_f32 v214, v126, v127
	v_lshlrev_b64 v[216:217], 1, v[230:231]
	v_lshl_add_u64 v[230:231], s[26:27], 0, v[216:217]
	v_mul_f32_e32 v127, v127, v127
	v_fmac_f32_e32 v127, v126, v126
	v_mul_f32_e32 v126, v129, v129
	v_fmac_f32_e32 v126, v128, v128
	v_pk_fma_f32 v[124:125], v[124:125], v[178:179], v[220:221] op_sel_hi:[1,0,1]
	v_pk_fma_f32 v[122:123], v[122:123], v[178:179], v[218:219] op_sel_hi:[1,0,1]
	v_cvt_pk_bf16_f32 v215, v128, v129
	global_store_dwordx2 v[230:231], v[214:215], off
	v_add_f32_e32 v183, v127, v126
	global_store_dwordx4 v[222:223], v[122:125], off offset:64 sc1
	v_cvt_pk_bf16_f32 v126, v122, v123
	v_or_b32_e32 v128, 32, v216
	v_mov_b32_e32 v129, v217
	v_mul_f32_e32 v123, v123, v123
	v_fmac_f32_e32 v123, v122, v122
	v_mul_f32_e32 v122, v125, v125
	v_fmac_f32_e32 v122, v124, v124
	v_lshl_add_u64 v[128:129], s[26:27], 0, v[128:129]
	v_add_f32_e32 v122, v123, v122
	v_pk_fma_f32 v[120:121], v[120:121], v[178:179], v[244:245] op_sel_hi:[1,0,1]
	v_pk_fma_f32 v[118:119], v[118:119], v[178:179], v[242:243] op_sel_hi:[1,0,1]
	v_cvt_pk_bf16_f32 v127, v124, v125
	global_store_dwordx2 v[128:129], v[126:127], off
	v_add_f32_e32 v126, v183, v122
	global_store_dwordx4 v[222:223], v[118:121], off offset:512 sc1
	v_cvt_pk_bf16_f32 v122, v118, v119
	v_pk_fma_f32 v[116:117], v[116:117], v[178:179], v[248:249] op_sel_hi:[1,0,1]
	v_pk_fma_f32 v[114:115], v[114:115], v[178:179], v[246:247] op_sel_hi:[1,0,1]
	v_mul_f32_e32 v119, v119, v119
	v_fmac_f32_e32 v119, v118, v118
	v_mul_f32_e32 v118, v121, v121
	v_fmac_f32_e32 v118, v120, v120
	v_cvt_pk_bf16_f32 v123, v120, v121
	v_add_f32_e32 v118, v119, v118
	v_mul_f32_e32 v119, v115, v115
	v_mul_f32_e32 v120, v117, v117
	v_fmac_f32_e32 v119, v114, v114
	v_fmac_f32_e32 v120, v116, v116
	v_add_f32_e32 v118, v118, v126
	v_add_f32_e32 v119, v119, v120
	v_add_f32_e32 v120, v119, v118
	ds_bpermute_b32 v121, v213, v120
	v_or_b32_e32 v124, 0x100, v216
	v_mov_b32_e32 v125, v217
	v_lshl_add_u64 v[124:125], s[26:27], 0, v[124:125]
	global_store_dwordx2 v[124:125], v[122:123], off
	global_store_dwordx4 v[222:223], v[114:117], off offset:576 sc1
	v_cvt_pk_bf16_f32 v118, v114, v115
	v_or_b32_e32 v216, 0x120, v216
	v_cvt_pk_bf16_f32 v119, v116, v117
	v_lshl_add_u32 v128, v179, 4, s0
	s_waitcnt lgkmcnt(0)
	v_add_f32_e32 v114, v120, v121
	ds_bpermute_b32 v115, v212, v114
	v_lshl_add_u64 v[116:117], s[26:27], 0, v[216:217]
	global_store_dwordx2 v[116:117], v[118:119], off
	s_and_saveexec_b64 s[0:1], vcc
	s_cbranch_execz .LBB0_1188
	s_waitcnt lgkmcnt(0)
	v_add_f32_e32 v114, v114, v115
	ds_write_b32 v128, v114
; __device__ __forceinline__ unsigned cvt_pk_bf16(float lo, float hi) { unsigned r; asm volatile("v_cvt_pk_bf16_f32 %0, %1, %2" : "=v"(r) : "v"(lo), "v"(hi)); return r; }
; __device__ __forceinline__ float bperm(float v, int srclane) { return __int_as_float(__builtin_amdgcn_ds_bpermute(srclane << 2, __float_as_int(v))); }
; __device__ __forceinline__ float bperm(float v, int srclane) { return __int_as_float(__builtin_amdgcn_ds_bpermute(srclane << 2, __float_as_int(v))); }
;     __device__ __forceinline__ void fused(f32x4 (&acc)[2][2][4][2], const Unit& u, int wr, int wc, int fr, int fq, PG8_LAS unsigned char* lds, int wid, int lane) const {
;     ...
;             for (int m = 0; m < 4; ++m) { const int row = row0 + ai * HALF + m * 16; float q = 0.f;
; #pragma unroll
;                 for (int bj = 0; bj < 2; ++bj)
; #pragma unroll
;                     for (int n = 0; n < 2; ++n) { const size_t off = (size_t)row * 1024 + col0 + bj * HALF + n * 16;
;                         f32x4 v = xv[m][bj][n] + acc[ai][bj][m][n] * scl; *(f32x4*)(x + off) = v;
;                         u32x2 w; w.x = cvt_pk_bf16(v[0], v[1]); w.y = cvt_pk_bf16(v[2], v[3]); *(u32x2*)(xb + off) = w;
;                         q += (v[0] * v[0] + v[1] * v[1]) + (v[2] * v[2] + v[3] * v[3]); }
;                 q += bperm(q, (fr + 16 * fq) ^ 16); q += bperm(q, (fr + 16 * fq) ^ 32);
;                 if (fq == 0) P[(ai * HALF + wr * 64 + m * 16 + fr) * 4 + wc] = q; }
.LBB0_1188:
	s_or_b64 exec, exec, s[0:1]
	s_waitcnt lgkmcnt(0)
	v_lshlrev_b64 v[114:115], 10, v[210:211]
	v_mov_b32_e32 v179, v178
	v_lshl_add_u64 v[116:117], v[114:115], 0, v[180:181]
	v_mov_b32_e32 v114, v178
	v_mov_b32_e32 v115, v178
	v_pk_fma_f32 v[112:113], v[112:113], v[114:115], v[176:177]
	v_pk_fma_f32 v[110:111], v[110:111], v[178:179], v[174:175]
	global_store_dwordx4 v[194:195], v[110:113], off sc1
	v_cvt_pk_bf16_f32 v118, v110, v111
	v_lshlrev_b64 v[116:117], 1, v[116:117]
	v_lshl_add_u64 v[120:121], s[26:27], 0, v[116:117]
	v_mul_f32_e32 v111, v111, v111
	v_fmac_f32_e32 v111, v110, v110
	v_mul_f32_e32 v110, v113, v113
	v_fmac_f32_e32 v110, v112, v112
	v_pk_fma_f32 v[108:109], v[108:109], v[114:115], v[172:173]
	v_pk_fma_f32 v[106:107], v[106:107], v[178:179], v[170:171]
	v_cvt_pk_bf16_f32 v119, v112, v113
	global_store_dwordx2 v[120:121], v[118:119], off
	v_add_f32_e32 v118, v111, v110
	global_store_dwordx4 v[194:195], v[106:109], off offset:64 sc1
	v_cvt_pk_bf16_f32 v110, v106, v107
	v_or_b32_e32 v112, 32, v116
	v_mov_b32_e32 v113, v117
	v_mul_f32_e32 v107, v107, v107
	v_fmac_f32_e32 v107, v106, v106
	v_mul_f32_e32 v106, v109, v109
	v_fmac_f32_e32 v106, v108, v108
	v_lshl_add_u64 v[112:113], s[26:27], 0, v[112:113]
	v_add_f32_e32 v106, v107, v106
	v_pk_fma_f32 v[104:105], v[104:105], v[114:115], v[168:169]
	v_pk_fma_f32 v[102:103], v[102:103], v[178:179], v[166:167]
	v_cvt_pk_bf16_f32 v111, v108, v109
	global_store_dwordx2 v[112:113], v[110:111], off
	v_add_f32_e32 v110, v118, v106
	global_store_dwordx4 v[194:195], v[102:105], off offset:512 sc1
	v_cvt_pk_bf16_f32 v106, v102, v103
	v_pk_fma_f32 v[100:101], v[100:101], v[114:115], v[164:165]
	v_pk_fma_f32 v[98:99], v[98:99], v[178:179], v[162:163]
	v_mul_f32_e32 v103, v103, v103
	v_fmac_f32_e32 v103, v102, v102
	v_mul_f32_e32 v102, v105, v105
	v_fmac_f32_e32 v102, v104, v104
	v_cvt_pk_bf16_f32 v107, v104, v105
	v_add_f32_e32 v102, v103, v102
	v_mul_f32_e32 v103, v99, v99
	v_mul_f32_e32 v104, v101, v101
	v_fmac_f32_e32 v103, v98, v98
	v_fmac_f32_e32 v104, v100, v100
	v_add_f32_e32 v102, v110, v102
	v_add_f32_e32 v103, v103, v104
	v_add_f32_e32 v104, v102, v103
	ds_bpermute_b32 v105, v213, v104
	v_or_b32_e32 v108, 0x100, v116
	v_mov_b32_e32 v109, v117
	v_lshl_add_u64 v[102:103], s[26:27], 0, v[108:109]
	global_store_dwordx2 v[102:103], v[106:107], off
	global_store_dwordx4 v[194:195], v[98:101], off offset:576 sc1
	v_cvt_pk_bf16_f32 v102, v98, v99
	v_or_b32_e32 v116, 0x120, v116
	v_cvt_pk_bf16_f32 v103, v100, v101
	s_waitcnt lgkmcnt(0)
	v_add_f32_e32 v98, v104, v105
	ds_bpermute_b32 v99, v212, v98
	v_lshl_add_u64 v[100:101], s[26:27], 0, v[116:117]
	global_store_dwordx2 v[100:101], v[102:103], off
	s_and_saveexec_b64 s[0:1], vcc
	s_cbranch_execz .LBB0_1190
	s_waitcnt lgkmcnt(0)
	v_add_f32_e32 v98, v98, v99
	ds_write_b32 v128, v98 offset:256
.LBB0_1190:
	s_or_b64 exec, exec, s[0:1]
	s_waitcnt lgkmcnt(0)
	v_lshlrev_b64 v[98:99], 10, v[192:193]
	v_pk_fma_f32 v[96:97], v[96:97], v[114:115], v[160:161]
	v_pk_fma_f32 v[94:95], v[94:95], v[178:179], v[158:159]
	v_lshl_add_u64 v[98:99], v[98:99], 0, v[180:181]
	global_store_dwordx4 v[190:191], v[94:97], off sc1
	v_cvt_pk_bf16_f32 v100, v94, v95
	v_lshlrev_b64 v[98:99], 1, v[98:99]
	v_lshl_add_u64 v[102:103], s[26:27], 0, v[98:99]
	v_mul_f32_e32 v95, v95, v95
	v_fmac_f32_e32 v95, v94, v94
	v_mul_f32_e32 v94, v97, v97
	v_fmac_f32_e32 v94, v96, v96
	v_pk_fma_f32 v[92:93], v[92:93], v[114:115], v[156:157]
	v_pk_fma_f32 v[90:91], v[90:91], v[178:179], v[154:155]
	v_cvt_pk_bf16_f32 v101, v96, v97
	global_store_dwordx2 v[102:103], v[100:101], off
	v_add_f32_e32 v100, v95, v94
	global_store_dwordx4 v[190:191], v[90:93], off offset:64 sc1
	v_cvt_pk_bf16_f32 v94, v90, v91
	v_or_b32_e32 v96, 32, v98
	v_mov_b32_e32 v97, v99
	v_mul_f32_e32 v91, v91, v91
	v_fmac_f32_e32 v91, v90, v90
	v_mul_f32_e32 v90, v93, v93
	v_fmac_f32_e32 v90, v92, v92
	v_lshl_add_u64 v[96:97], s[26:27], 0, v[96:97]
	v_add_f32_e32 v90, v91, v90
	v_pk_fma_f32 v[88:89], v[88:89], v[114:115], v[152:153]
	v_pk_fma_f32 v[86:87], v[86:87], v[178:179], v[150:151]
	v_cvt_pk_bf16_f32 v95, v92, v93
	global_store_dwordx2 v[96:97], v[94:95], off
	v_add_f32_e32 v94, v100, v90
	global_store_dwordx4 v[190:191], v[86:89], off offset:512 sc1
	v_cvt_pk_bf16_f32 v90, v86, v87
	v_pk_fma_f32 v[84:85], v[84:85], v[114:115], v[148:149]
	v_pk_fma_f32 v[82:83], v[82:83], v[178:179], v[146:147]
	v_mul_f32_e32 v87, v87, v87
	v_fmac_f32_e32 v87, v86, v86
	v_mul_f32_e32 v86, v89, v89
	v_fmac_f32_e32 v86, v88, v88
	v_cvt_pk_bf16_f32 v91, v88, v89
	v_add_f32_e32 v86, v87, v86
	v_mul_f32_e32 v87, v83, v83
	v_mul_f32_e32 v88, v85, v85
	v_fmac_f32_e32 v87, v82, v82
	v_fmac_f32_e32 v88, v84, v84
	v_add_f32_e32 v86, v94, v86
	v_add_f32_e32 v87, v87, v88
	v_add_f32_e32 v88, v86, v87
	ds_bpermute_b32 v89, v213, v88
	v_or_b32_e32 v92, 0x100, v98
	v_mov_b32_e32 v93, v99
	v_lshl_add_u64 v[86:87], s[26:27], 0, v[92:93]
	global_store_dwordx2 v[86:87], v[90:91], off
	global_store_dwordx4 v[190:191], v[82:85], off offset:576 sc1
	v_cvt_pk_bf16_f32 v86, v82, v83
	v_or_b32_e32 v98, 0x120, v98
	v_cvt_pk_bf16_f32 v87, v84, v85
	s_waitcnt lgkmcnt(0)
	v_add_f32_e32 v82, v88, v89
	ds_bpermute_b32 v83, v212, v82
	v_lshl_add_u64 v[84:85], s[26:27], 0, v[98:99]
	global_store_dwordx2 v[84:85], v[86:87], off
	s_and_saveexec_b64 s[0:1], vcc
	s_cbranch_execz .LBB0_1192
	s_waitcnt lgkmcnt(0)
	v_add_f32_e32 v82, v82, v83
	ds_write_b32 v128, v82 offset:512
; __device__ __forceinline__ unsigned cvt_pk_bf16(float lo, float hi) { unsigned r; asm volatile("v_cvt_pk_bf16_f32 %0, %1, %2" : "=v"(r) : "v"(lo), "v"(hi)); return r; }
; __device__ __forceinline__ float bperm(float v, int srclane) { return __int_as_float(__builtin_amdgcn_ds_bpermute(srclane << 2, __float_as_int(v))); }
; __device__ __forceinline__ float bperm(float v, int srclane) { return __int_as_float(__builtin_amdgcn_ds_bpermute(srclane << 2, __float_as_int(v))); }
;     __device__ __forceinline__ void fused(f32x4 (&acc)[2][2][4][2], const Unit& u, int wr, int wc, int fr, int fq, PG8_LAS unsigned char* lds, int wid, int lane) const {
;     ...
;                     for (int n = 0; n < 2; ++n) xv[m][bj][n] = *(const f32x4*)(xin + (size_t)(row0 + ai * HALF + m * 16) * 1024 + col0 + bj * HALF + n * 16);
;             __builtin_amdgcn_sched_barrier(0);
; #pragma unroll
;             for (int m = 0; m < 4; ++m) { const int row = row0 + ai * HALF + m * 16; float q = 0.f;
; #pragma unroll
;                 for (int bj = 0; bj < 2; ++bj)
; #pragma unroll
;                     for (int n = 0; n < 2; ++n) { const size_t off = (size_t)row * 1024 + col0 + bj * HALF + n * 16;
;                         f32x4 v = xv[m][bj][n] + acc[ai][bj][m][n] * scl; *(f32x4*)(x + off) = v;
;                         u32x2 w; w.x = cvt_pk_bf16(v[0], v[1]); w.y = cvt_pk_bf16(v[2], v[3]); *(u32x2*)(xb + off) = w;
;                         q += (v[0] * v[0] + v[1] * v[1]) + (v[2] * v[2] + v[3] * v[3]); }
;                 q += bperm(q, (fr + 16 * fq) ^ 16); q += bperm(q, (fr + 16 * fq) ^ 32);
;                 if (fq == 0) P[(ai * HALF + wr * 64 + m * 16 + fr) * 4 + wc] = q; }
.LBB0_1192:
	s_or_b64 exec, exec, s[0:1]
	v_mov_b32_e32 v124, v178
	v_mov_b32_e32 v125, v178
	s_waitcnt lgkmcnt(0)
	v_lshlrev_b64 v[82:83], 10, v[188:189]
	v_pk_fma_f32 v[80:81], v[80:81], v[124:125], v[144:145]
	v_pk_fma_f32 v[78:79], v[78:79], v[178:179], v[142:143]
	v_lshl_add_u64 v[82:83], v[82:83], 0, v[180:181]
	global_store_dwordx4 v[186:187], v[78:81], off sc1
	v_cvt_pk_bf16_f32 v84, v78, v79
	v_lshlrev_b64 v[82:83], 1, v[82:83]
	v_lshl_add_u64 v[86:87], s[26:27], 0, v[82:83]
	v_mul_f32_e32 v79, v79, v79
	v_fmac_f32_e32 v79, v78, v78
	v_mul_f32_e32 v78, v81, v81
	v_fmac_f32_e32 v78, v80, v80
	v_pk_fma_f32 v[76:77], v[76:77], v[124:125], v[140:141]
	v_pk_fma_f32 v[74:75], v[74:75], v[178:179], v[138:139]
	v_cvt_pk_bf16_f32 v85, v80, v81
	global_store_dwordx2 v[86:87], v[84:85], off
	v_add_f32_e32 v84, v79, v78
	global_store_dwordx4 v[186:187], v[74:77], off offset:64 sc1
	v_cvt_pk_bf16_f32 v78, v74, v75
	v_or_b32_e32 v80, 32, v82
	v_mov_b32_e32 v81, v83
	v_mul_f32_e32 v75, v75, v75
	v_fmac_f32_e32 v75, v74, v74
	v_mul_f32_e32 v74, v77, v77
	v_fmac_f32_e32 v74, v76, v76
	v_lshl_add_u64 v[80:81], s[26:27], 0, v[80:81]
	v_add_f32_e32 v74, v75, v74
	v_pk_fma_f32 v[72:73], v[72:73], v[124:125], v[136:137]
	v_pk_fma_f32 v[70:71], v[70:71], v[178:179], v[134:135]
	v_cvt_pk_bf16_f32 v79, v76, v77
	global_store_dwordx2 v[80:81], v[78:79], off
	v_add_f32_e32 v78, v84, v74
	global_store_dwordx4 v[186:187], v[70:73], off offset:512 sc1
	v_cvt_pk_bf16_f32 v74, v70, v71
	v_pk_fma_f32 v[68:69], v[68:69], v[124:125], v[132:133]
	v_pk_fma_f32 v[66:67], v[66:67], v[178:179], v[130:131]
	v_mul_f32_e32 v71, v71, v71
	v_fmac_f32_e32 v71, v70, v70
	v_mul_f32_e32 v70, v73, v73
	v_fmac_f32_e32 v70, v72, v72
	v_cvt_pk_bf16_f32 v75, v72, v73
	v_add_f32_e32 v70, v71, v70
	v_mul_f32_e32 v71, v67, v67
	v_mul_f32_e32 v72, v69, v69
	v_fmac_f32_e32 v71, v66, v66
	v_fmac_f32_e32 v72, v68, v68
	v_add_f32_e32 v70, v78, v70
	v_add_f32_e32 v71, v71, v72
	v_add_f32_e32 v72, v70, v71
	ds_bpermute_b32 v73, v213, v72
	v_or_b32_e32 v76, 0x100, v82
	v_mov_b32_e32 v77, v83
	v_lshl_add_u64 v[70:71], s[26:27], 0, v[76:77]
	global_store_dwordx2 v[70:71], v[74:75], off
	global_store_dwordx4 v[186:187], v[66:69], off offset:576 sc1
	v_cvt_pk_bf16_f32 v70, v66, v67
	v_or_b32_e32 v82, 0x120, v82
	v_cvt_pk_bf16_f32 v71, v68, v69
	s_waitcnt lgkmcnt(0)
	v_add_f32_e32 v66, v72, v73
	ds_bpermute_b32 v67, v212, v66
	v_lshl_add_u64 v[68:69], s[26:27], 0, v[82:83]
	global_store_dwordx2 v[68:69], v[70:71], off
	s_and_saveexec_b64 s[0:1], vcc
	s_cbranch_execz .LBB0_1194
	s_waitcnt lgkmcnt(0)
	v_add_f32_e32 v66, v66, v67
	ds_write_b32 v128, v66 offset:768
.LBB0_1194:
	s_or_b64 exec, exec, s[0:1]
	v_add_u32_e32 v146, 0x80, v182
	v_ashrrev_i32_e32 v147, 31, v146
	v_add_u32_e32 v126, 0x90, v182
	s_waitcnt lgkmcnt(0)
	v_lshlrev_b64 v[66:67], 12, v[146:147]
	v_ashrrev_i32_e32 v127, 31, v126
	v_add_u32_e32 v120, 0xa0, v182
	v_lshl_add_u64 v[148:149], v[184:185], 0, v[66:67]
	v_lshlrev_b64 v[66:67], 12, v[126:127]
	v_ashrrev_i32_e32 v121, 31, v120
	v_add_u32_e32 v116, 0xb0, v182
	v_lshl_add_u64 v[122:123], v[184:185], 0, v[66:67]
	v_lshlrev_b64 v[66:67], 12, v[120:121]
	v_ashrrev_i32_e32 v117, 31, v116
	v_lshl_add_u64 v[118:119], v[184:185], 0, v[66:67]
	v_lshlrev_b64 v[66:67], 12, v[116:117]
	v_lshl_add_u64 v[114:115], v[184:185], 0, v[66:67]
	global_load_dwordx4 v[130:133], v[148:149], off
	global_load_dwordx4 v[134:137], v[148:149], off offset:64
	global_load_dwordx4 v[138:141], v[148:149], off offset:512
	global_load_dwordx4 v[142:145], v[148:149], off offset:576
	global_load_dwordx4 v[110:113], v[122:123], off
	global_load_dwordx4 v[106:109], v[122:123], off offset:64
	global_load_dwordx4 v[102:105], v[122:123], off offset:512
	global_load_dwordx4 v[98:101], v[122:123], off offset:576
	global_load_dwordx4 v[94:97], v[118:119], off
	global_load_dwordx4 v[90:93], v[118:119], off offset:64
	global_load_dwordx4 v[86:89], v[118:119], off offset:512
	global_load_dwordx4 v[82:85], v[118:119], off offset:576
	global_load_dwordx4 v[78:81], v[114:115], off
	global_load_dwordx4 v[74:77], v[114:115], off offset:64
	global_load_dwordx4 v[70:73], v[114:115], off offset:512
	global_load_dwordx4 v[66:69], v[114:115], off offset:576
	v_lshlrev_b64 v[146:147], 10, v[146:147]
	s_waitcnt vmcnt(15)
	v_pk_fma_f32 v[62:63], v[62:63], v[124:125], v[132:133]
	v_pk_fma_f32 v[60:61], v[60:61], v[178:179], v[130:131]
	v_lshl_add_u64 v[146:147], v[146:147], 0, v[180:181]
	global_store_dwordx4 v[148:149], v[60:63], off sc1
	v_cvt_pk_bf16_f32 v130, v60, v61
	v_lshlrev_b64 v[132:133], 1, v[146:147]
	v_lshl_add_u64 v[146:147], s[26:27], 0, v[132:133]
	v_mul_f32_e32 v61, v61, v61
	v_fmac_f32_e32 v61, v60, v60
	v_mul_f32_e32 v60, v63, v63
	v_fmac_f32_e32 v60, v62, v62
	s_waitcnt vmcnt(15)
	v_pk_fma_f32 v[58:59], v[58:59], v[124:125], v[136:137]
	v_pk_fma_f32 v[56:57], v[56:57], v[178:179], v[134:135]
	v_cvt_pk_bf16_f32 v131, v62, v63
	global_store_dwordx2 v[146:147], v[130:131], off
	v_add_f32_e32 v129, v61, v60
	global_store_dwordx4 v[148:149], v[56:59], off offset:64 sc1
	v_cvt_pk_bf16_f32 v60, v56, v57
	v_or_b32_e32 v62, 32, v132
	v_mov_b32_e32 v63, v133
	v_mul_f32_e32 v57, v57, v57
	v_fmac_f32_e32 v57, v56, v56
	v_mul_f32_e32 v56, v59, v59
	v_fmac_f32_e32 v56, v58, v58
	v_lshl_add_u64 v[62:63], s[26:27], 0, v[62:63]
	v_add_f32_e32 v56, v57, v56
	s_waitcnt vmcnt(16)
	v_pk_fma_f32 v[54:55], v[54:55], v[124:125], v[140:141]
	v_pk_fma_f32 v[52:53], v[52:53], v[178:179], v[138:139]
	v_cvt_pk_bf16_f32 v61, v58, v59
	global_store_dwordx2 v[62:63], v[60:61], off
	v_add_f32_e32 v60, v129, v56
	global_store_dwordx4 v[148:149], v[52:55], off offset:512 sc1
	v_cvt_pk_bf16_f32 v56, v52, v53
	s_waitcnt vmcnt(17)
	v_pk_fma_f32 v[50:51], v[50:51], v[124:125], v[144:145]
	v_pk_fma_f32 v[48:49], v[48:49], v[178:179], v[142:143]
	v_mul_f32_e32 v53, v53, v53
	v_fmac_f32_e32 v53, v52, v52
	v_mul_f32_e32 v52, v55, v55
	v_fmac_f32_e32 v52, v54, v54
	v_cvt_pk_bf16_f32 v57, v54, v55
	v_add_f32_e32 v52, v53, v52
	v_mul_f32_e32 v53, v49, v49
	v_mul_f32_e32 v54, v51, v51
	v_fmac_f32_e32 v53, v48, v48
	v_fmac_f32_e32 v54, v50, v50
	v_add_f32_e32 v52, v60, v52
	v_add_f32_e32 v53, v53, v54
	v_add_f32_e32 v54, v52, v53
	ds_bpermute_b32 v55, v213, v54
	v_or_b32_e32 v58, 0x100, v132
	v_mov_b32_e32 v59, v133
	v_lshl_add_u64 v[52:53], s[26:27], 0, v[58:59]
	global_store_dwordx2 v[52:53], v[56:57], off
	global_store_dwordx4 v[148:149], v[48:51], off offset:576 sc1
	v_cvt_pk_bf16_f32 v52, v48, v49
	v_or_b32_e32 v132, 0x120, v132
	v_cvt_pk_bf16_f32 v53, v50, v51
	s_waitcnt lgkmcnt(0)
	v_add_f32_e32 v48, v54, v55
	ds_bpermute_b32 v49, v212, v48
	v_lshl_add_u64 v[50:51], s[26:27], 0, v[132:133]
	global_store_dwordx2 v[50:51], v[52:53], off
	s_and_saveexec_b64 s[0:1], vcc
	s_cbranch_execz .LBB0_1196
	s_waitcnt lgkmcnt(0)
	v_add_f32_e32 v48, v48, v49
	ds_write_b32 v128, v48 offset:2048
; __device__ __forceinline__ unsigned cvt_pk_bf16(float lo, float hi) { unsigned r; asm volatile("v_cvt_pk_bf16_f32 %0, %1, %2" : "=v"(r) : "v"(lo), "v"(hi)); return r; }
; __device__ __forceinline__ float bperm(float v, int srclane) { return __int_as_float(__builtin_amdgcn_ds_bpermute(srclane << 2, __float_as_int(v))); }
; __device__ __forceinline__ float bperm(float v, int srclane) { return __int_as_float(__builtin_amdgcn_ds_bpermute(srclane << 2, __float_as_int(v))); }
;     __device__ __forceinline__ void fused(f32x4 (&acc)[2][2][4][2], const Unit& u, int wr, int wc, int fr, int fq, PG8_LAS unsigned char* lds, int wid, int lane) const {
;     ...
;             for (int m = 0; m < 4; ++m) { const int row = row0 + ai * HALF + m * 16; float q = 0.f;
; #pragma unroll
;                 for (int bj = 0; bj < 2; ++bj)
; #pragma unroll
;                     for (int n = 0; n < 2; ++n) { const size_t off = (size_t)row * 1024 + col0 + bj * HALF + n * 16;
;                         f32x4 v = xv[m][bj][n] + acc[ai][bj][m][n] * scl; *(f32x4*)(x + off) = v;
;                         u32x2 w; w.x = cvt_pk_bf16(v[0], v[1]); w.y = cvt_pk_bf16(v[2], v[3]); *(u32x2*)(xb + off) = w;
;                         q += (v[0] * v[0] + v[1] * v[1]) + (v[2] * v[2] + v[3] * v[3]); }
;                 q += bperm(q, (fr + 16 * fq) ^ 16); q += bperm(q, (fr + 16 * fq) ^ 32);
;                 if (fq == 0) P[(ai * HALF + wr * 64 + m * 16 + fr) * 4 + wc] = q; }
.LBB0_1196:
	s_or_b64 exec, exec, s[0:1]
	s_waitcnt lgkmcnt(0)
	v_lshlrev_b64 v[48:49], 10, v[126:127]
	v_lshl_add_u64 v[50:51], v[48:49], 0, v[180:181]
	v_mov_b32_e32 v48, v178
	v_mov_b32_e32 v49, v178
	s_waitcnt vmcnt(19)
	v_pk_fma_f32 v[46:47], v[46:47], v[48:49], v[112:113]
	v_pk_fma_f32 v[44:45], v[44:45], v[178:179], v[110:111]
	global_store_dwordx4 v[122:123], v[44:47], off sc1
	v_cvt_pk_bf16_f32 v52, v44, v45
	v_lshlrev_b64 v[50:51], 1, v[50:51]
	v_lshl_add_u64 v[54:55], s[26:27], 0, v[50:51]
	v_mul_f32_e32 v45, v45, v45
	v_fmac_f32_e32 v45, v44, v44
	v_mul_f32_e32 v44, v47, v47
	v_fmac_f32_e32 v44, v46, v46
	s_waitcnt vmcnt(19)
	v_pk_fma_f32 v[42:43], v[42:43], v[48:49], v[108:109]
	v_pk_fma_f32 v[40:41], v[40:41], v[178:179], v[106:107]
	v_cvt_pk_bf16_f32 v53, v46, v47
	global_store_dwordx2 v[54:55], v[52:53], off
	v_add_f32_e32 v52, v45, v44
	global_store_dwordx4 v[122:123], v[40:43], off offset:64 sc1
	v_cvt_pk_bf16_f32 v44, v40, v41
	v_or_b32_e32 v46, 32, v50
	v_mov_b32_e32 v47, v51
	v_mul_f32_e32 v41, v41, v41
	v_fmac_f32_e32 v41, v40, v40
	v_mul_f32_e32 v40, v43, v43
	v_fmac_f32_e32 v40, v42, v42
	v_lshl_add_u64 v[46:47], s[26:27], 0, v[46:47]
	v_add_f32_e32 v40, v41, v40
	s_waitcnt vmcnt(20)
	v_pk_fma_f32 v[38:39], v[38:39], v[48:49], v[104:105]
	v_pk_fma_f32 v[36:37], v[36:37], v[178:179], v[102:103]
	v_cvt_pk_bf16_f32 v45, v42, v43
	global_store_dwordx2 v[46:47], v[44:45], off
	v_add_f32_e32 v44, v52, v40
	global_store_dwordx4 v[122:123], v[36:39], off offset:512 sc1
	v_cvt_pk_bf16_f32 v40, v36, v37
	s_waitcnt vmcnt(21)
	v_pk_fma_f32 v[34:35], v[34:35], v[48:49], v[100:101]
	v_pk_fma_f32 v[32:33], v[32:33], v[178:179], v[98:99]
	v_mul_f32_e32 v37, v37, v37
	v_fmac_f32_e32 v37, v36, v36
	v_mul_f32_e32 v36, v39, v39
	v_fmac_f32_e32 v36, v38, v38
	v_cvt_pk_bf16_f32 v41, v38, v39
	v_add_f32_e32 v36, v37, v36
	v_mul_f32_e32 v37, v33, v33
	v_mul_f32_e32 v38, v35, v35
	v_fmac_f32_e32 v37, v32, v32
	v_fmac_f32_e32 v38, v34, v34
	v_add_f32_e32 v36, v44, v36
	v_add_f32_e32 v37, v37, v38
	v_add_f32_e32 v38, v36, v37
	ds_bpermute_b32 v39, v213, v38
	v_or_b32_e32 v42, 0x100, v50
	v_mov_b32_e32 v43, v51
	v_lshl_add_u64 v[36:37], s[26:27], 0, v[42:43]
	global_store_dwordx2 v[36:37], v[40:41], off
	global_store_dwordx4 v[122:123], v[32:35], off offset:576 sc1
	v_cvt_pk_bf16_f32 v36, v32, v33
	v_or_b32_e32 v50, 0x120, v50
	v_cvt_pk_bf16_f32 v37, v34, v35
	s_waitcnt lgkmcnt(0)
	v_add_f32_e32 v32, v38, v39
	ds_bpermute_b32 v33, v212, v32
	v_lshl_add_u64 v[34:35], s[26:27], 0, v[50:51]
	global_store_dwordx2 v[34:35], v[36:37], off
	s_and_saveexec_b64 s[0:1], vcc
	s_cbranch_execz .LBB0_1198
	s_waitcnt lgkmcnt(0)
	v_add_f32_e32 v32, v32, v33
	ds_write_b32 v128, v32 offset:2304
; __device__ __forceinline__ unsigned cvt_pk_bf16(float lo, float hi) { unsigned r; asm volatile("v_cvt_pk_bf16_f32 %0, %1, %2" : "=v"(r) : "v"(lo), "v"(hi)); return r; }
; __device__ __forceinline__ float bperm(float v, int srclane) { return __int_as_float(__builtin_amdgcn_ds_bpermute(srclane << 2, __float_as_int(v))); }
; __device__ __forceinline__ float bperm(float v, int srclane) { return __int_as_float(__builtin_amdgcn_ds_bpermute(srclane << 2, __float_as_int(v))); }
;     __device__ __forceinline__ void fused(f32x4 (&acc)[2][2][4][2], const Unit& u, int wr, int wc, int fr, int fq, PG8_LAS unsigned char* lds, int wid, int lane) const {
;     ...
;             for (int m = 0; m < 4; ++m) { const int row = row0 + ai * HALF + m * 16; float q = 0.f;
; #pragma unroll
;                 for (int bj = 0; bj < 2; ++bj)
; #pragma unroll
;                     for (int n = 0; n < 2; ++n) { const size_t off = (size_t)row * 1024 + col0 + bj * HALF + n * 16;
;                         f32x4 v = xv[m][bj][n] + acc[ai][bj][m][n] * scl; *(f32x4*)(x + off) = v;
;                         u32x2 w; w.x = cvt_pk_bf16(v[0], v[1]); w.y = cvt_pk_bf16(v[2], v[3]); *(u32x2*)(xb + off) = w;
;                         q += (v[0] * v[0] + v[1] * v[1]) + (v[2] * v[2] + v[3] * v[3]); }
;                 q += bperm(q, (fr + 16 * fq) ^ 16); q += bperm(q, (fr + 16 * fq) ^ 32);
;                 if (fq == 0) P[(ai * HALF + wr * 64 + m * 16 + fr) * 4 + wc] = q; }
.LBB0_1198:
	s_or_b64 exec, exec, s[0:1]
	s_waitcnt lgkmcnt(0)
	v_lshlrev_b64 v[32:33], 10, v[120:121]
	s_waitcnt vmcnt(23)
	v_pk_fma_f32 v[30:31], v[30:31], v[48:49], v[96:97]
	v_pk_fma_f32 v[28:29], v[28:29], v[178:179], v[94:95]
	v_lshl_add_u64 v[32:33], v[32:33], 0, v[180:181]
	global_store_dwordx4 v[118:119], v[28:31], off sc1
	v_cvt_pk_bf16_f32 v34, v28, v29
	v_lshlrev_b64 v[32:33], 1, v[32:33]
	v_lshl_add_u64 v[36:37], s[26:27], 0, v[32:33]
	v_mul_f32_e32 v29, v29, v29
	v_fmac_f32_e32 v29, v28, v28
	v_mul_f32_e32 v28, v31, v31
	v_fmac_f32_e32 v28, v30, v30
	s_waitcnt vmcnt(23)
	v_pk_fma_f32 v[26:27], v[26:27], v[48:49], v[92:93]
	v_pk_fma_f32 v[24:25], v[24:25], v[178:179], v[90:91]
	v_cvt_pk_bf16_f32 v35, v30, v31
	global_store_dwordx2 v[36:37], v[34:35], off
	v_add_f32_e32 v34, v29, v28
	global_store_dwordx4 v[118:119], v[24:27], off offset:64 sc1
	v_cvt_pk_bf16_f32 v28, v24, v25
	v_or_b32_e32 v30, 32, v32
	v_mov_b32_e32 v31, v33
	v_mul_f32_e32 v25, v25, v25
	v_fmac_f32_e32 v25, v24, v24
	v_mul_f32_e32 v24, v27, v27
	v_fmac_f32_e32 v24, v26, v26
	v_lshl_add_u64 v[30:31], s[26:27], 0, v[30:31]
	v_add_f32_e32 v24, v25, v24
	s_waitcnt vmcnt(24)
	v_pk_fma_f32 v[22:23], v[22:23], v[48:49], v[88:89]
	v_pk_fma_f32 v[20:21], v[20:21], v[178:179], v[86:87]
	v_cvt_pk_bf16_f32 v29, v26, v27
	global_store_dwordx2 v[30:31], v[28:29], off
	v_add_f32_e32 v28, v34, v24
	global_store_dwordx4 v[118:119], v[20:23], off offset:512 sc1
	v_cvt_pk_bf16_f32 v24, v20, v21
	s_waitcnt vmcnt(25)
	v_pk_fma_f32 v[18:19], v[18:19], v[48:49], v[84:85]
	v_pk_fma_f32 v[16:17], v[16:17], v[178:179], v[82:83]
	v_mul_f32_e32 v21, v21, v21
	v_fmac_f32_e32 v21, v20, v20
	v_mul_f32_e32 v20, v23, v23
	v_fmac_f32_e32 v20, v22, v22
	v_cvt_pk_bf16_f32 v25, v22, v23
	v_add_f32_e32 v20, v21, v20
	v_mul_f32_e32 v21, v17, v17
	v_mul_f32_e32 v22, v19, v19
	v_fmac_f32_e32 v21, v16, v16
	v_fmac_f32_e32 v22, v18, v18
	v_add_f32_e32 v20, v28, v20
	v_add_f32_e32 v21, v21, v22
	v_add_f32_e32 v22, v20, v21
	ds_bpermute_b32 v23, v213, v22
	v_or_b32_e32 v26, 0x100, v32
	v_mov_b32_e32 v27, v33
	v_lshl_add_u64 v[20:21], s[26:27], 0, v[26:27]
	global_store_dwordx2 v[20:21], v[24:25], off
	global_store_dwordx4 v[118:119], v[16:19], off offset:576 sc1
	v_cvt_pk_bf16_f32 v20, v16, v17
	v_or_b32_e32 v32, 0x120, v32
	v_cvt_pk_bf16_f32 v21, v18, v19
	s_waitcnt lgkmcnt(0)
	v_add_f32_e32 v16, v22, v23
	ds_bpermute_b32 v17, v212, v16
	v_lshl_add_u64 v[18:19], s[26:27], 0, v[32:33]
	global_store_dwordx2 v[18:19], v[20:21], off
	s_and_saveexec_b64 s[0:1], vcc
	s_cbranch_execz .LBB0_1200
	s_waitcnt lgkmcnt(0)
	v_add_f32_e32 v16, v16, v17
	ds_write_b32 v128, v16 offset:2560
.LBB0_1200:
	s_or_b64 exec, exec, s[0:1]
	v_mov_b32_e32 v18, v178
	v_mov_b32_e32 v19, v178
	s_waitcnt lgkmcnt(0)
	v_lshlrev_b64 v[16:17], 10, v[116:117]
	s_waitcnt vmcnt(27)
	v_pk_fma_f32 v[14:15], v[14:15], v[18:19], v[80:81]
	v_pk_fma_f32 v[12:13], v[12:13], v[178:179], v[78:79]
	v_lshl_add_u64 v[16:17], v[16:17], 0, v[180:181]
	global_store_dwordx4 v[114:115], v[12:15], off sc1
	v_cvt_pk_bf16_f32 v20, v12, v13
	v_lshlrev_b64 v[16:17], 1, v[16:17]
	v_lshl_add_u64 v[22:23], s[26:27], 0, v[16:17]
	v_mul_f32_e32 v13, v13, v13
	v_fmac_f32_e32 v13, v12, v12
	v_mul_f32_e32 v12, v15, v15
	v_fmac_f32_e32 v12, v14, v14
	s_waitcnt vmcnt(27)
	v_pk_fma_f32 v[10:11], v[10:11], v[18:19], v[76:77]
	v_pk_fma_f32 v[8:9], v[8:9], v[178:179], v[74:75]
	v_cvt_pk_bf16_f32 v21, v14, v15
	global_store_dwordx2 v[22:23], v[20:21], off
	v_add_f32_e32 v20, v13, v12
	global_store_dwordx4 v[114:115], v[8:11], off offset:64 sc1
	v_cvt_pk_bf16_f32 v12, v8, v9
	v_or_b32_e32 v14, 32, v16
	v_mov_b32_e32 v15, v17
	v_mul_f32_e32 v9, v9, v9
	v_fmac_f32_e32 v9, v8, v8
	v_mul_f32_e32 v8, v11, v11
	v_fmac_f32_e32 v8, v10, v10
	v_lshl_add_u64 v[14:15], s[26:27], 0, v[14:15]
	v_add_f32_e32 v8, v9, v8
	s_waitcnt vmcnt(28)
	v_pk_fma_f32 v[6:7], v[6:7], v[18:19], v[72:73]
	v_pk_fma_f32 v[4:5], v[4:5], v[178:179], v[70:71]
	v_cvt_pk_bf16_f32 v13, v10, v11
	global_store_dwordx2 v[14:15], v[12:13], off
	v_add_f32_e32 v12, v20, v8
	global_store_dwordx4 v[114:115], v[4:7], off offset:512 sc1
	v_cvt_pk_bf16_f32 v8, v4, v5
	s_waitcnt vmcnt(29)
	v_pk_fma_f32 v[2:3], v[2:3], v[18:19], v[68:69]
	v_pk_fma_f32 v[0:1], v[0:1], v[178:179], v[66:67]
	v_mul_f32_e32 v5, v5, v5
	v_fmac_f32_e32 v5, v4, v4
	v_mul_f32_e32 v4, v7, v7
	v_fmac_f32_e32 v4, v6, v6
	v_cvt_pk_bf16_f32 v9, v6, v7
	v_add_f32_e32 v4, v5, v4
	v_mul_f32_e32 v5, v1, v1
	v_mul_f32_e32 v6, v3, v3
	v_fmac_f32_e32 v5, v0, v0
	v_fmac_f32_e32 v6, v2, v2
	v_add_f32_e32 v4, v12, v4
	v_add_f32_e32 v5, v5, v6
	v_add_f32_e32 v6, v4, v5
	ds_bpermute_b32 v7, v213, v6
	v_or_b32_e32 v10, 0x100, v16
	v_mov_b32_e32 v11, v17
	v_lshl_add_u64 v[4:5], s[26:27], 0, v[10:11]
	global_store_dwordx2 v[4:5], v[8:9], off
	global_store_dwordx4 v[114:115], v[0:3], off offset:576 sc1
	v_cvt_pk_bf16_f32 v4, v0, v1
	v_or_b32_e32 v16, 0x120, v16
	v_cvt_pk_bf16_f32 v5, v2, v3
	s_waitcnt lgkmcnt(0)
	v_add_f32_e32 v0, v6, v7
	ds_bpermute_b32 v1, v212, v0
	v_lshl_add_u64 v[2:3], s[26:27], 0, v[16:17]
	global_store_dwordx2 v[2:3], v[4:5], off
	s_and_saveexec_b64 s[0:1], vcc
	s_cbranch_execz .LBB0_1202
	s_waitcnt lgkmcnt(0)
	v_add_f32_e32 v0, v0, v1
	ds_write_b32 v128, v0 offset:2816

; #define PG8_LAS __attribute__((address_space(3)))
; __device__ __forceinline__ unsigned cvt_pk_bf16(float lo, float hi) { unsigned r; asm volatile("v_cvt_pk_bf16_f32 %0, %1, %2" : "=v"(r) : "v"(lo), "v"(hi)); return r; }
; __device__ __forceinline__ float bperm(float v, int srclane) { return __int_as_float(__builtin_amdgcn_ds_bpermute(srclane << 2, __float_as_int(v))); }
; __device__ __forceinline__ float bperm(float v, int srclane) { return __int_as_float(__builtin_amdgcn_ds_bpermute(srclane << 2, __float_as_int(v))); }
;     __device__ __forceinline__ void fused(f32x4 (&acc)[2][2][4][2], const Unit& u, int wr, int wc, int fr, int fq, PG8_LAS unsigned char* lds, int wid, int lane) const {
;         float scl = scale; asm volatile("" : "+v"(scl)); const int row0 = u.pm * BM + wr * 64 + fr, col0 = u.pn * BM + wc * 32 + 4 * fq;
;         PG8_LAS float* P = (PG8_LAS float*)lds;
; #pragma unroll
;         for (int ai = 0; ai < 2; ++ai) { f32x4 xv[4][2][2];
; #pragma unroll
;             for (int m = 0; m < 4; ++m)
; #pragma unroll
;                 for (int bj = 0; bj < 2; ++bj)
; #pragma unroll
;                     for (int n = 0; n < 2; ++n) xv[m][bj][n] = *(const f32x4*)(xin + (size_t)(row0 + ai * HALF + m * 16) * 1024 + col0 + bj * HALF + n * 16);
;             __builtin_amdgcn_sched_barrier(0);
; #pragma unroll
;             for (int m = 0; m < 4; ++m) { const int row = row0 + ai * HALF + m * 16; float q = 0.f;
; #pragma unroll
;                 for (int bj = 0; bj < 2; ++bj)
; #pragma unroll
;                     for (int n = 0; n < 2; ++n) { const size_t off = (size_t)row * 1024 + col0 + bj * HALF + n * 16;
;                         f32x4 v = xv[m][bj][n] + acc[ai][bj][m][n] * scl; *(f32x4*)(x + off) = v;
;                         u32x2 w; w.x = cvt_pk_bf16(v[0], v[1]); w.y = cvt_pk_bf16(v[2], v[3]); *(u32x2*)(xb + off) = w;
;                         q += (v[0] * v[0] + v[1] * v[1]) + (v[2] * v[2] + v[3] * v[3]); }
;                 q += bperm(q, (fr + 16 * fq) ^ 16); q += bperm(q, (fr + 16 * fq) ^ 32);
;                 if (fq == 0) P[(ai * HALF + wr * 64 + m * 16 + fr) * 4 + wc] = q; }
.LBB0_1371:
	s_lshl_b32 s0, s24, 5
	s_lshl_b32 s2, s68, 8
	s_lshl_b32 s1, s64, 8
	v_bfe_u32 v130, v136, 4, 2
	s_add_i32 s30, s30, s2
	s_or_b32 s0, s0, s1
	v_or_b32_e32 v182, s30, v138
	v_lshl_or_b32 v180, v130, 2, s0
	v_ashrrev_i32_e32 v181, 31, v180
	v_lshlrev_b32_e32 v130, 6, v130
	v_ashrrev_i32_e32 v183, 31, v182
	v_or_b32_e32 v210, 16, v182
	v_bitop3_b32 v213, v130, 64, v137 bitop3:0x36
	v_bitop3_b32 v212, v130, s93, v137 bitop3:0x36
	v_lshl_add_u64 v[184:185], v[180:181], 2, s[76:77]
	v_lshlrev_b64 v[130:131], 12, v[182:183]
	v_ashrrev_i32_e32 v211, 31, v210
	v_or_b32_e32 v192, 32, v182
	v_lshl_add_u64 v[222:223], v[184:185], 0, v[130:131]
	v_lshlrev_b64 v[130:131], 12, v[210:211]
	v_ashrrev_i32_e32 v193, 31, v192
	v_or_b32_e32 v188, 48, v182
	v_lshl_add_u64 v[194:195], v[184:185], 0, v[130:131]
	v_lshlrev_b64 v[130:131], 12, v[192:193]
	v_ashrrev_i32_e32 v189, 31, v188
	v_lshl_add_u64 v[190:191], v[184:185], 0, v[130:131]
	v_lshlrev_b64 v[130:131], 12, v[188:189]
	v_mov_b32_e32 v178, 1.0
	v_lshl_add_u64 v[186:187], v[184:185], 0, v[130:131]
	v_and_b32_e32 v64, 63, v136
	s_barrier
	global_load_dwordx4 v[214:217], v[222:223], off
	global_load_dwordx4 v[218:221], v[222:223], off offset:64
	global_load_dwordx4 v[242:245], v[222:223], off offset:512
	global_load_dwordx4 v[246:249], v[222:223], off offset:576
	global_load_dwordx4 v[174:177], v[194:195], off
	global_load_dwordx4 v[170:173], v[194:195], off offset:64
	global_load_dwordx4 v[166:169], v[194:195], off offset:512
	global_load_dwordx4 v[162:165], v[194:195], off offset:576
	global_load_dwordx4 v[158:161], v[190:191], off
	global_load_dwordx4 v[154:157], v[190:191], off offset:64
	global_load_dwordx4 v[150:153], v[190:191], off offset:512
	global_load_dwordx4 v[146:149], v[190:191], off offset:576
	global_load_dwordx4 v[142:145], v[186:187], off
	global_load_dwordx4 v[138:141], v[186:187], off offset:64
	global_load_dwordx4 v[134:137], v[186:187], off offset:512
	global_load_dwordx4 v[130:133], v[186:187], off offset:576
	s_lshl_b32 s0, s24, 2
	s_add_i32 s0, s0, 0
	v_cmp_gt_u32_e32 vcc, 16, v64
	v_lshlrev_b64 v[230:231], 10, v[182:183]
	s_waitcnt vmcnt(0)
	v_pk_fma_f32 v[128:129], v[128:129], v[178:179], v[216:217] op_sel_hi:[1,0,1]
	v_pk_fma_f32 v[126:127], v[126:127], v[178:179], v[214:215] op_sel_hi:[1,0,1]
	v_lshl_add_u64 v[230:231], v[230:231], 0, v[180:181]
	global_store_dwordx4 v[222:223], v[126:129], off sc1
	v_cvt_pk_bf16_f32 v214, v126, v127
	v_lshlrev_b64 v[216:217], 1, v[230:231]
	v_lshl_add_u64 v[230:231], s[26:27], 0, v[216:217]
	v_mul_f32_e32 v127, v127, v127
	v_fmac_f32_e32 v127, v126, v126
	v_mul_f32_e32 v126, v129, v129
	v_fmac_f32_e32 v126, v128, v128
	v_pk_fma_f32 v[124:125], v[124:125], v[178:179], v[220:221] op_sel_hi:[1,0,1]
	v_pk_fma_f32 v[122:123], v[122:123], v[178:179], v[218:219] op_sel_hi:[1,0,1]
	v_cvt_pk_bf16_f32 v215, v128, v129
	global_store_dwordx2 v[230:231], v[214:215], off
	v_add_f32_e32 v183, v127, v126
	global_store_dwordx4 v[222:223], v[122:125], off offset:64 sc1
	v_cvt_pk_bf16_f32 v126, v122, v123
	v_or_b32_e32 v128, 32, v216
	v_mov_b32_e32 v129, v217
	v_mul_f32_e32 v123, v123, v123
	v_fmac_f32_e32 v123, v122, v122
	v_mul_f32_e32 v122, v125, v125
	v_fmac_f32_e32 v122, v124, v124
	v_lshl_add_u64 v[128:129], s[26:27], 0, v[128:129]
	v_add_f32_e32 v122, v123, v122
	v_pk_fma_f32 v[120:121], v[120:121], v[178:179], v[244:245] op_sel_hi:[1,0,1]
	v_pk_fma_f32 v[118:119], v[118:119], v[178:179], v[242:243] op_sel_hi:[1,0,1]
	v_cvt_pk_bf16_f32 v127, v124, v125
	global_store_dwordx2 v[128:129], v[126:127], off
	v_add_f32_e32 v126, v183, v122
	global_store_dwordx4 v[222:223], v[118:121], off offset:512 sc1
	v_cvt_pk_bf16_f32 v122, v118, v119
	v_pk_fma_f32 v[116:117], v[116:117], v[178:179], v[248:249] op_sel_hi:[1,0,1]
	v_pk_fma_f32 v[114:115], v[114:115], v[178:179], v[246:247] op_sel_hi:[1,0,1]
	v_mul_f32_e32 v119, v119, v119
	v_fmac_f32_e32 v119, v118, v118
	v_mul_f32_e32 v118, v121, v121
	v_fmac_f32_e32 v118, v120, v120
	v_cvt_pk_bf16_f32 v123, v120, v121
	v_add_f32_e32 v118, v119, v118
	v_mul_f32_e32 v119, v115, v115
	v_mul_f32_e32 v120, v117, v117
	v_fmac_f32_e32 v119, v114, v114
	v_fmac_f32_e32 v120, v116, v116
	v_add_f32_e32 v118, v118, v126
	v_add_f32_e32 v119, v119, v120
	v_add_f32_e32 v120, v119, v118
	ds_bpermute_b32 v121, v213, v120
	v_or_b32_e32 v124, 0x100, v216
	v_mov_b32_e32 v125, v217
	v_lshl_add_u64 v[124:125], s[26:27], 0, v[124:125]
	global_store_dwordx2 v[124:125], v[122:123], off
	global_store_dwordx4 v[222:223], v[114:117], off offset:576 sc1
	v_cvt_pk_bf16_f32 v118, v114, v115
	v_or_b32_e32 v216, 0x120, v216
	v_cvt_pk_bf16_f32 v119, v116, v117
	v_lshl_add_u32 v128, v179, 4, s0
	s_waitcnt lgkmcnt(0)
	v_add_f32_e32 v114, v120, v121
	ds_bpermute_b32 v115, v212, v114
	v_lshl_add_u64 v[116:117], s[26:27], 0, v[216:217]
	global_store_dwordx2 v[116:117], v[118:119], off
	s_and_saveexec_b64 s[0:1], vcc
	s_cbranch_execz .LBB0_1373
	s_waitcnt lgkmcnt(0)
	v_add_f32_e32 v114, v114, v115
	ds_write_b32 v128, v114

; #define PG8_LAS __attribute__((address_space(3)))
; __device__ __forceinline__ unsigned cvt_pk_bf16(float lo, float hi) { unsigned r; asm volatile("v_cvt_pk_bf16_f32 %0, %1, %2" : "=v"(r) : "v"(lo), "v"(hi)); return r; }
; __device__ __forceinline__ float bperm(float v, int srclane) { return __int_as_float(__builtin_amdgcn_ds_bpermute(srclane << 2, __float_as_int(v))); }
; __device__ __forceinline__ float bperm(float v, int srclane) { return __int_as_float(__builtin_amdgcn_ds_bpermute(srclane << 2, __float_as_int(v))); }
;     __device__ __forceinline__ void fused(f32x4 (&acc)[2][2][4][2], const Unit& u, int wr, int wc, int fr, int fq, PG8_LAS unsigned char* lds, int wid, int lane) const {
;         float scl = scale; asm volatile("" : "+v"(scl)); const int row0 = u.pm * BM + wr * 64 + fr, col0 = u.pn * BM + wc * 32 + 4 * fq;
;         PG8_LAS float* P = (PG8_LAS float*)lds;
; #pragma unroll
;         for (int ai = 0; ai < 2; ++ai) { f32x4 xv[4][2][2];
; #pragma unroll
;             for (int m = 0; m < 4; ++m)
; #pragma unroll
;                 for (int bj = 0; bj < 2; ++bj)
; #pragma unroll
;                     for (int n = 0; n < 2; ++n) xv[m][bj][n] = *(const f32x4*)(xin + (size_t)(row0 + ai * HALF + m * 16) * 1024 + col0 + bj * HALF + n * 16);
;             __builtin_amdgcn_sched_barrier(0);
; #pragma unroll
;             for (int m = 0; m < 4; ++m) { const int row = row0 + ai * HALF + m * 16; float q = 0.f;
; #pragma unroll
;                 for (int bj = 0; bj < 2; ++bj)
; #pragma unroll
;                     for (int n = 0; n < 2; ++n) { const size_t off = (size_t)row * 1024 + col0 + bj * HALF + n * 16;
;                         f32x4 v = xv[m][bj][n] + acc[ai][bj][m][n] * scl; *(f32x4*)(x + off) = v;
;                         u32x2 w; w.x = cvt_pk_bf16(v[0], v[1]); w.y = cvt_pk_bf16(v[2], v[3]); *(u32x2*)(xb + off) = w;
;                         q += (v[0] * v[0] + v[1] * v[1]) + (v[2] * v[2] + v[3] * v[3]); }
;                 q += bperm(q, (fr + 16 * fq) ^ 16); q += bperm(q, (fr + 16 * fq) ^ 32);
;                 if (fq == 0) P[(ai * HALF + wr * 64 + m * 16 + fr) * 4 + wc] = q; }
.LBB0_1525:
	s_lshl_b32 s2, s23, 5
	s_lshl_b32 s4, s63, 8
	s_lshl_b32 s3, s70, 8
	v_bfe_u32 v130, v136, 4, 2
	s_add_i32 s25, s25, s4
	s_or_b32 s2, s2, s3
	v_or_b32_e32 v182, s25, v138
	v_lshl_or_b32 v180, v130, 2, s2
	v_ashrrev_i32_e32 v181, 31, v180
	v_lshlrev_b32_e32 v130, 6, v130
	v_ashrrev_i32_e32 v183, 31, v182
	v_or_b32_e32 v210, 16, v182
	v_bitop3_b32 v213, v130, 64, v137 bitop3:0x36
	v_bitop3_b32 v212, v130, s93, v137 bitop3:0x36
	v_lshl_add_u64 v[184:185], v[180:181], 2, s[76:77]
	v_lshlrev_b64 v[130:131], 12, v[182:183]
	v_ashrrev_i32_e32 v211, 31, v210
	v_or_b32_e32 v192, 32, v182
	v_lshl_add_u64 v[222:223], v[184:185], 0, v[130:131]
	v_lshlrev_b64 v[130:131], 12, v[210:211]
	v_ashrrev_i32_e32 v193, 31, v192
	v_or_b32_e32 v188, 48, v182
	v_lshl_add_u64 v[194:195], v[184:185], 0, v[130:131]
	v_lshlrev_b64 v[130:131], 12, v[192:193]
	v_ashrrev_i32_e32 v189, 31, v188
	v_lshl_add_u64 v[190:191], v[184:185], 0, v[130:131]
	v_lshlrev_b64 v[130:131], 12, v[188:189]
	v_mov_b32_e32 v178, 0.5
	v_lshl_add_u64 v[186:187], v[184:185], 0, v[130:131]
	v_and_b32_e32 v64, 63, v136
	s_barrier
	global_load_dwordx4 v[214:217], v[222:223], off
	global_load_dwordx4 v[218:221], v[222:223], off offset:64
	global_load_dwordx4 v[242:245], v[222:223], off offset:512
	global_load_dwordx4 v[246:249], v[222:223], off offset:576
	global_load_dwordx4 v[174:177], v[194:195], off
	global_load_dwordx4 v[170:173], v[194:195], off offset:64
	global_load_dwordx4 v[166:169], v[194:195], off offset:512
	global_load_dwordx4 v[162:165], v[194:195], off offset:576
	global_load_dwordx4 v[158:161], v[190:191], off
	global_load_dwordx4 v[154:157], v[190:191], off offset:64
	global_load_dwordx4 v[150:153], v[190:191], off offset:512
	global_load_dwordx4 v[146:149], v[190:191], off offset:576
	global_load_dwordx4 v[142:145], v[186:187], off
	global_load_dwordx4 v[138:141], v[186:187], off offset:64
	global_load_dwordx4 v[134:137], v[186:187], off offset:512
	global_load_dwordx4 v[130:133], v[186:187], off offset:576
	s_lshl_b32 s2, s23, 2
	s_add_i32 s2, s2, 0
	v_cmp_gt_u32_e32 vcc, 16, v64
	v_lshlrev_b64 v[230:231], 10, v[182:183]
	s_waitcnt vmcnt(0)
	v_pk_fma_f32 v[128:129], v[128:129], v[178:179], v[216:217] op_sel_hi:[1,0,1]
	v_pk_fma_f32 v[126:127], v[126:127], v[178:179], v[214:215] op_sel_hi:[1,0,1]
	v_lshl_add_u64 v[230:231], v[230:231], 0, v[180:181]
	global_store_dwordx4 v[222:223], v[126:129], off sc1
	v_cvt_pk_bf16_f32 v214, v126, v127
	v_lshlrev_b64 v[216:217], 1, v[230:231]
	v_lshl_add_u64 v[230:231], s[26:27], 0, v[216:217]
	v_mul_f32_e32 v127, v127, v127
	v_fmac_f32_e32 v127, v126, v126
	v_mul_f32_e32 v126, v129, v129
	v_fmac_f32_e32 v126, v128, v128
	v_pk_fma_f32 v[124:125], v[124:125], v[178:179], v[220:221] op_sel_hi:[1,0,1]
	v_pk_fma_f32 v[122:123], v[122:123], v[178:179], v[218:219] op_sel_hi:[1,0,1]
	v_cvt_pk_bf16_f32 v215, v128, v129
	global_store_dwordx2 v[230:231], v[214:215], off
	v_add_f32_e32 v183, v127, v126
	global_store_dwordx4 v[222:223], v[122:125], off offset:64 sc1
	v_cvt_pk_bf16_f32 v126, v122, v123
	v_or_b32_e32 v128, 32, v216
	v_mov_b32_e32 v129, v217
	v_mul_f32_e32 v123, v123, v123
	v_fmac_f32_e32 v123, v122, v122
	v_mul_f32_e32 v122, v125, v125
	v_fmac_f32_e32 v122, v124, v124
	v_lshl_add_u64 v[128:129], s[26:27], 0, v[128:129]
	v_add_f32_e32 v122, v123, v122
	v_pk_fma_f32 v[120:121], v[120:121], v[178:179], v[244:245] op_sel_hi:[1,0,1]
	v_pk_fma_f32 v[118:119], v[118:119], v[178:179], v[242:243] op_sel_hi:[1,0,1]
	v_cvt_pk_bf16_f32 v127, v124, v125
	global_store_dwordx2 v[128:129], v[126:127], off
	v_add_f32_e32 v126, v183, v122
	global_store_dwordx4 v[222:223], v[118:121], off offset:512 sc1
	v_cvt_pk_bf16_f32 v122, v118, v119
	v_pk_fma_f32 v[116:117], v[116:117], v[178:179], v[248:249] op_sel_hi:[1,0,1]
	v_pk_fma_f32 v[114:115], v[114:115], v[178:179], v[246:247] op_sel_hi:[1,0,1]
	v_mul_f32_e32 v119, v119, v119
	v_fmac_f32_e32 v119, v118, v118
	v_mul_f32_e32 v118, v121, v121
	v_fmac_f32_e32 v118, v120, v120
	v_cvt_pk_bf16_f32 v123, v120, v121
	v_add_f32_e32 v118, v119, v118
	v_mul_f32_e32 v119, v115, v115
	v_mul_f32_e32 v120, v117, v117
	v_fmac_f32_e32 v119, v114, v114
	v_fmac_f32_e32 v120, v116, v116
	v_add_f32_e32 v118, v118, v126
	v_add_f32_e32 v119, v119, v120
	v_add_f32_e32 v120, v119, v118
	ds_bpermute_b32 v121, v213, v120
	v_or_b32_e32 v124, 0x100, v216
	v_mov_b32_e32 v125, v217
	v_lshl_add_u64 v[124:125], s[26:27], 0, v[124:125]
	global_store_dwordx2 v[124:125], v[122:123], off
	global_store_dwordx4 v[222:223], v[114:117], off offset:576 sc1
	v_cvt_pk_bf16_f32 v118, v114, v115
	v_or_b32_e32 v216, 0x120, v216
	v_cvt_pk_bf16_f32 v119, v116, v117
	v_lshl_add_u32 v128, v179, 4, s2
	s_waitcnt lgkmcnt(0)
	v_add_f32_e32 v114, v120, v121
	ds_bpermute_b32 v115, v212, v114
	v_lshl_add_u64 v[116:117], s[26:27], 0, v[216:217]
	global_store_dwordx2 v[116:117], v[118:119], off
	s_and_saveexec_b64 s[2:3], vcc
	s_cbranch_execz .LBB0_1527
	s_waitcnt lgkmcnt(0)
	v_add_f32_e32 v114, v114, v115
	ds_write_b32 v128, v114
; __device__ __forceinline__ unsigned cvt_pk_bf16(float lo, float hi) { unsigned r; asm volatile("v_cvt_pk_bf16_f32 %0, %1, %2" : "=v"(r) : "v"(lo), "v"(hi)); return r; }
; __device__ __forceinline__ float bperm(float v, int srclane) { return __int_as_float(__builtin_amdgcn_ds_bpermute(srclane << 2, __float_as_int(v))); }
; __device__ __forceinline__ float bperm(float v, int srclane) { return __int_as_float(__builtin_amdgcn_ds_bpermute(srclane << 2, __float_as_int(v))); }
;     __device__ __forceinline__ void fused(f32x4 (&acc)[2][2][4][2], const Unit& u, int wr, int wc, int fr, int fq, PG8_LAS unsigned char* lds, int wid, int lane) const {
;     ...
;             for (int m = 0; m < 4; ++m) { const int row = row0 + ai * HALF + m * 16; float q = 0.f;
; #pragma unroll
;                 for (int bj = 0; bj < 2; ++bj)
; #pragma unroll
;                     for (int n = 0; n < 2; ++n) { const size_t off = (size_t)row * 1024 + col0 + bj * HALF + n * 16;
;                         f32x4 v = xv[m][bj][n] + acc[ai][bj][m][n] * scl; *(f32x4*)(x + off) = v;
;                         u32x2 w; w.x = cvt_pk_bf16(v[0], v[1]); w.y = cvt_pk_bf16(v[2], v[3]); *(u32x2*)(xb + off) = w;
;                         q += (v[0] * v[0] + v[1] * v[1]) + (v[2] * v[2] + v[3] * v[3]); }
;                 q += bperm(q, (fr + 16 * fq) ^ 16); q += bperm(q, (fr + 16 * fq) ^ 32);
;                 if (fq == 0) P[(ai * HALF + wr * 64 + m * 16 + fr) * 4 + wc] = q; }
.LBB0_1527:
	s_or_b64 exec, exec, s[2:3]
	s_waitcnt lgkmcnt(0)
	v_lshlrev_b64 v[114:115], 10, v[210:211]
	v_mov_b32_e32 v179, v178
	v_lshl_add_u64 v[116:117], v[114:115], 0, v[180:181]
	v_mov_b32_e32 v114, v178
	v_mov_b32_e32 v115, v178
	v_pk_fma_f32 v[112:113], v[112:113], v[114:115], v[176:177]
	v_pk_fma_f32 v[110:111], v[110:111], v[178:179], v[174:175]
	global_store_dwordx4 v[194:195], v[110:113], off sc1
	v_cvt_pk_bf16_f32 v118, v110, v111
	v_lshlrev_b64 v[116:117], 1, v[116:117]
	v_lshl_add_u64 v[120:121], s[26:27], 0, v[116:117]
	v_mul_f32_e32 v111, v111, v111
	v_fmac_f32_e32 v111, v110, v110
	v_mul_f32_e32 v110, v113, v113
	v_fmac_f32_e32 v110, v112, v112
	v_pk_fma_f32 v[108:109], v[108:109], v[114:115], v[172:173]
	v_pk_fma_f32 v[106:107], v[106:107], v[178:179], v[170:171]
	v_cvt_pk_bf16_f32 v119, v112, v113
	global_store_dwordx2 v[120:121], v[118:119], off
	v_add_f32_e32 v118, v111, v110
	global_store_dwordx4 v[194:195], v[106:109], off offset:64 sc1
	v_cvt_pk_bf16_f32 v110, v106, v107
	v_or_b32_e32 v112, 32, v116
	v_mov_b32_e32 v113, v117
	v_mul_f32_e32 v107, v107, v107
	v_fmac_f32_e32 v107, v106, v106
	v_mul_f32_e32 v106, v109, v109
	v_fmac_f32_e32 v106, v108, v108
	v_lshl_add_u64 v[112:113], s[26:27], 0, v[112:113]
	v_add_f32_e32 v106, v107, v106
	v_pk_fma_f32 v[104:105], v[104:105], v[114:115], v[168:169]
	v_pk_fma_f32 v[102:103], v[102:103], v[178:179], v[166:167]
	v_cvt_pk_bf16_f32 v111, v108, v109
	global_store_dwordx2 v[112:113], v[110:111], off
	v_add_f32_e32 v110, v118, v106
	global_store_dwordx4 v[194:195], v[102:105], off offset:512 sc1
	v_cvt_pk_bf16_f32 v106, v102, v103
	v_pk_fma_f32 v[100:101], v[100:101], v[114:115], v[164:165]
	v_pk_fma_f32 v[98:99], v[98:99], v[178:179], v[162:163]
	v_mul_f32_e32 v103, v103, v103
	v_fmac_f32_e32 v103, v102, v102
	v_mul_f32_e32 v102, v105, v105
	v_fmac_f32_e32 v102, v104, v104
	v_cvt_pk_bf16_f32 v107, v104, v105
	v_add_f32_e32 v102, v103, v102
	v_mul_f32_e32 v103, v99, v99
	v_mul_f32_e32 v104, v101, v101
	v_fmac_f32_e32 v103, v98, v98
	v_fmac_f32_e32 v104, v100, v100
	v_add_f32_e32 v102, v110, v102
	v_add_f32_e32 v103, v103, v104
	v_add_f32_e32 v104, v102, v103
	ds_bpermute_b32 v105, v213, v104
	v_or_b32_e32 v108, 0x100, v116
	v_mov_b32_e32 v109, v117
	v_lshl_add_u64 v[102:103], s[26:27], 0, v[108:109]
	global_store_dwordx2 v[102:103], v[106:107], off
	global_store_dwordx4 v[194:195], v[98:101], off offset:576 sc1
	v_cvt_pk_bf16_f32 v102, v98, v99
	v_or_b32_e32 v116, 0x120, v116
	v_cvt_pk_bf16_f32 v103, v100, v101
	s_waitcnt lgkmcnt(0)
	v_add_f32_e32 v98, v104, v105
	ds_bpermute_b32 v99, v212, v98
	v_lshl_add_u64 v[100:101], s[26:27], 0, v[116:117]
	global_store_dwordx2 v[100:101], v[102:103], off
	s_and_saveexec_b64 s[2:3], vcc
	s_cbranch_execz .LBB0_1529
	s_waitcnt lgkmcnt(0)
	v_add_f32_e32 v98, v98, v99
	ds_write_b32 v128, v98 offset:256
.LBB0_1529:
	s_or_b64 exec, exec, s[2:3]
	s_waitcnt lgkmcnt(0)
	v_lshlrev_b64 v[98:99], 10, v[192:193]
	v_pk_fma_f32 v[96:97], v[96:97], v[114:115], v[160:161]
	v_pk_fma_f32 v[94:95], v[94:95], v[178:179], v[158:159]
	v_lshl_add_u64 v[98:99], v[98:99], 0, v[180:181]
	global_store_dwordx4 v[190:191], v[94:97], off sc1
	v_cvt_pk_bf16_f32 v100, v94, v95
	v_lshlrev_b64 v[98:99], 1, v[98:99]
	v_lshl_add_u64 v[102:103], s[26:27], 0, v[98:99]
	v_mul_f32_e32 v95, v95, v95
	v_fmac_f32_e32 v95, v94, v94
	v_mul_f32_e32 v94, v97, v97
	v_fmac_f32_e32 v94, v96, v96
	v_pk_fma_f32 v[92:93], v[92:93], v[114:115], v[156:157]
	v_pk_fma_f32 v[90:91], v[90:91], v[178:179], v[154:155]
	v_cvt_pk_bf16_f32 v101, v96, v97
	global_store_dwordx2 v[102:103], v[100:101], off
	v_add_f32_e32 v100, v95, v94
	global_store_dwordx4 v[190:191], v[90:93], off offset:64 sc1
	v_cvt_pk_bf16_f32 v94, v90, v91
	v_or_b32_e32 v96, 32, v98
	v_mov_b32_e32 v97, v99
	v_mul_f32_e32 v91, v91, v91
	v_fmac_f32_e32 v91, v90, v90
	v_mul_f32_e32 v90, v93, v93
	v_fmac_f32_e32 v90, v92, v92
	v_lshl_add_u64 v[96:97], s[26:27], 0, v[96:97]
	v_add_f32_e32 v90, v91, v90
	v_pk_fma_f32 v[88:89], v[88:89], v[114:115], v[152:153]
	v_pk_fma_f32 v[86:87], v[86:87], v[178:179], v[150:151]
	v_cvt_pk_bf16_f32 v95, v92, v93
	global_store_dwordx2 v[96:97], v[94:95], off
	v_add_f32_e32 v94, v100, v90
	global_store_dwordx4 v[190:191], v[86:89], off offset:512 sc1
	v_cvt_pk_bf16_f32 v90, v86, v87
	v_pk_fma_f32 v[84:85], v[84:85], v[114:115], v[148:149]
	v_pk_fma_f32 v[82:83], v[82:83], v[178:179], v[146:147]
	v_mul_f32_e32 v87, v87, v87
	v_fmac_f32_e32 v87, v86, v86
	v_mul_f32_e32 v86, v89, v89
	v_fmac_f32_e32 v86, v88, v88
	v_cvt_pk_bf16_f32 v91, v88, v89
	v_add_f32_e32 v86, v87, v86
	v_mul_f32_e32 v87, v83, v83
	v_mul_f32_e32 v88, v85, v85
	v_fmac_f32_e32 v87, v82, v82
	v_fmac_f32_e32 v88, v84, v84
	v_add_f32_e32 v86, v94, v86
	v_add_f32_e32 v87, v87, v88
	v_add_f32_e32 v88, v86, v87
	ds_bpermute_b32 v89, v213, v88
	v_or_b32_e32 v92, 0x100, v98
	v_mov_b32_e32 v93, v99
	v_lshl_add_u64 v[86:87], s[26:27], 0, v[92:93]
	global_store_dwordx2 v[86:87], v[90:91], off
	global_store_dwordx4 v[190:191], v[82:85], off offset:576 sc1
	v_cvt_pk_bf16_f32 v86, v82, v83
	v_or_b32_e32 v98, 0x120, v98
	v_cvt_pk_bf16_f32 v87, v84, v85
	s_waitcnt lgkmcnt(0)
	v_add_f32_e32 v82, v88, v89
	ds_bpermute_b32 v83, v212, v82
	v_lshl_add_u64 v[84:85], s[26:27], 0, v[98:99]
	global_store_dwordx2 v[84:85], v[86:87], off
	s_and_saveexec_b64 s[2:3], vcc
	s_cbranch_execz .LBB0_1531
	s_waitcnt lgkmcnt(0)
	v_add_f32_e32 v82, v82, v83
	ds_write_b32 v128, v82 offset:512
; __device__ __forceinline__ unsigned cvt_pk_bf16(float lo, float hi) { unsigned r; asm volatile("v_cvt_pk_bf16_f32 %0, %1, %2" : "=v"(r) : "v"(lo), "v"(hi)); return r; }
; __device__ __forceinline__ float bperm(float v, int srclane) { return __int_as_float(__builtin_amdgcn_ds_bpermute(srclane << 2, __float_as_int(v))); }
; __device__ __forceinline__ float bperm(float v, int srclane) { return __int_as_float(__builtin_amdgcn_ds_bpermute(srclane << 2, __float_as_int(v))); }
;     __device__ __forceinline__ void fused(f32x4 (&acc)[2][2][4][2], const Unit& u, int wr, int wc, int fr, int fq, PG8_LAS unsigned char* lds, int wid, int lane) const {
;     ...
;                     for (int n = 0; n < 2; ++n) xv[m][bj][n] = *(const f32x4*)(xin + (size_t)(row0 + ai * HALF + m * 16) * 1024 + col0 + bj * HALF + n * 16);
;             __builtin_amdgcn_sched_barrier(0);
; #pragma unroll
;             for (int m = 0; m < 4; ++m) { const int row = row0 + ai * HALF + m * 16; float q = 0.f;
; #pragma unroll
;                 for (int bj = 0; bj < 2; ++bj)
; #pragma unroll
;                     for (int n = 0; n < 2; ++n) { const size_t off = (size_t)row * 1024 + col0 + bj * HALF + n * 16;
;                         f32x4 v = xv[m][bj][n] + acc[ai][bj][m][n] * scl; *(f32x4*)(x + off) = v;
;                         u32x2 w; w.x = cvt_pk_bf16(v[0], v[1]); w.y = cvt_pk_bf16(v[2], v[3]); *(u32x2*)(xb + off) = w;
;                         q += (v[0] * v[0] + v[1] * v[1]) + (v[2] * v[2] + v[3] * v[3]); }
;                 q += bperm(q, (fr + 16 * fq) ^ 16); q += bperm(q, (fr + 16 * fq) ^ 32);
;                 if (fq == 0) P[(ai * HALF + wr * 64 + m * 16 + fr) * 4 + wc] = q; }
.LBB0_1531:
	s_or_b64 exec, exec, s[2:3]
	v_mov_b32_e32 v124, v178
	v_mov_b32_e32 v125, v178
	s_waitcnt lgkmcnt(0)
	v_lshlrev_b64 v[82:83], 10, v[188:189]
	v_pk_fma_f32 v[80:81], v[80:81], v[124:125], v[144:145]
	v_pk_fma_f32 v[78:79], v[78:79], v[178:179], v[142:143]
	v_lshl_add_u64 v[82:83], v[82:83], 0, v[180:181]
	global_store_dwordx4 v[186:187], v[78:81], off sc1
	v_cvt_pk_bf16_f32 v84, v78, v79
	v_lshlrev_b64 v[82:83], 1, v[82:83]
	v_lshl_add_u64 v[86:87], s[26:27], 0, v[82:83]
	v_mul_f32_e32 v79, v79, v79
	v_fmac_f32_e32 v79, v78, v78
	v_mul_f32_e32 v78, v81, v81
	v_fmac_f32_e32 v78, v80, v80
	v_pk_fma_f32 v[76:77], v[76:77], v[124:125], v[140:141]
	v_pk_fma_f32 v[74:75], v[74:75], v[178:179], v[138:139]
	v_cvt_pk_bf16_f32 v85, v80, v81
	global_store_dwordx2 v[86:87], v[84:85], off
	v_add_f32_e32 v84, v79, v78
	global_store_dwordx4 v[186:187], v[74:77], off offset:64 sc1
	v_cvt_pk_bf16_f32 v78, v74, v75
	v_or_b32_e32 v80, 32, v82
	v_mov_b32_e32 v81, v83
	v_mul_f32_e32 v75, v75, v75
	v_fmac_f32_e32 v75, v74, v74
	v_mul_f32_e32 v74, v77, v77
	v_fmac_f32_e32 v74, v76, v76
	v_lshl_add_u64 v[80:81], s[26:27], 0, v[80:81]
	v_add_f32_e32 v74, v75, v74
	v_pk_fma_f32 v[72:73], v[72:73], v[124:125], v[136:137]
	v_pk_fma_f32 v[70:71], v[70:71], v[178:179], v[134:135]
	v_cvt_pk_bf16_f32 v79, v76, v77
	global_store_dwordx2 v[80:81], v[78:79], off
	v_add_f32_e32 v78, v84, v74
	global_store_dwordx4 v[186:187], v[70:73], off offset:512 sc1
	v_cvt_pk_bf16_f32 v74, v70, v71
	v_pk_fma_f32 v[68:69], v[68:69], v[124:125], v[132:133]
	v_pk_fma_f32 v[66:67], v[66:67], v[178:179], v[130:131]
	v_mul_f32_e32 v71, v71, v71
	v_fmac_f32_e32 v71, v70, v70
	v_mul_f32_e32 v70, v73, v73
	v_fmac_f32_e32 v70, v72, v72
	v_cvt_pk_bf16_f32 v75, v72, v73
	v_add_f32_e32 v70, v71, v70
	v_mul_f32_e32 v71, v67, v67
	v_mul_f32_e32 v72, v69, v69
	v_fmac_f32_e32 v71, v66, v66
	v_fmac_f32_e32 v72, v68, v68
	v_add_f32_e32 v70, v78, v70
	v_add_f32_e32 v71, v71, v72
	v_add_f32_e32 v72, v70, v71
	ds_bpermute_b32 v73, v213, v72
	v_or_b32_e32 v76, 0x100, v82
	v_mov_b32_e32 v77, v83
	v_lshl_add_u64 v[70:71], s[26:27], 0, v[76:77]
	global_store_dwordx2 v[70:71], v[74:75], off
	global_store_dwordx4 v[186:187], v[66:69], off offset:576 sc1
	v_cvt_pk_bf16_f32 v70, v66, v67
	v_or_b32_e32 v82, 0x120, v82
	v_cvt_pk_bf16_f32 v71, v68, v69
	s_waitcnt lgkmcnt(0)
	v_add_f32_e32 v66, v72, v73
	ds_bpermute_b32 v67, v212, v66
	v_lshl_add_u64 v[68:69], s[26:27], 0, v[82:83]
	global_store_dwordx2 v[68:69], v[70:71], off
	s_and_saveexec_b64 s[2:3], vcc
	s_cbranch_execz .LBB0_1533
	s_waitcnt lgkmcnt(0)
	v_add_f32_e32 v66, v66, v67
	ds_write_b32 v128, v66 offset:768
.LBB0_1533:
	s_or_b64 exec, exec, s[2:3]
	v_add_u32_e32 v146, 0x80, v182
	v_ashrrev_i32_e32 v147, 31, v146
	v_add_u32_e32 v126, 0x90, v182
	s_waitcnt lgkmcnt(0)
	v_lshlrev_b64 v[66:67], 12, v[146:147]
	v_ashrrev_i32_e32 v127, 31, v126
	v_add_u32_e32 v120, 0xa0, v182
	v_lshl_add_u64 v[148:149], v[184:185], 0, v[66:67]
	v_lshlrev_b64 v[66:67], 12, v[126:127]
	v_ashrrev_i32_e32 v121, 31, v120
	v_add_u32_e32 v116, 0xb0, v182
	v_lshl_add_u64 v[122:123], v[184:185], 0, v[66:67]
	v_lshlrev_b64 v[66:67], 12, v[120:121]
	v_ashrrev_i32_e32 v117, 31, v116
	v_lshl_add_u64 v[118:119], v[184:185], 0, v[66:67]
	v_lshlrev_b64 v[66:67], 12, v[116:117]
	v_lshl_add_u64 v[114:115], v[184:185], 0, v[66:67]
	global_load_dwordx4 v[130:133], v[148:149], off
	global_load_dwordx4 v[134:137], v[148:149], off offset:64
	global_load_dwordx4 v[138:141], v[148:149], off offset:512
	global_load_dwordx4 v[142:145], v[148:149], off offset:576
	global_load_dwordx4 v[110:113], v[122:123], off
	global_load_dwordx4 v[106:109], v[122:123], off offset:64
	global_load_dwordx4 v[102:105], v[122:123], off offset:512
	global_load_dwordx4 v[98:101], v[122:123], off offset:576
	global_load_dwordx4 v[94:97], v[118:119], off
	global_load_dwordx4 v[90:93], v[118:119], off offset:64
	global_load_dwordx4 v[86:89], v[118:119], off offset:512
	global_load_dwordx4 v[82:85], v[118:119], off offset:576
	global_load_dwordx4 v[78:81], v[114:115], off
	global_load_dwordx4 v[74:77], v[114:115], off offset:64
	global_load_dwordx4 v[70:73], v[114:115], off offset:512
	global_load_dwordx4 v[66:69], v[114:115], off offset:576
	v_lshlrev_b64 v[146:147], 10, v[146:147]
	s_waitcnt vmcnt(15)
	v_pk_fma_f32 v[62:63], v[62:63], v[124:125], v[132:133]
	v_pk_fma_f32 v[60:61], v[60:61], v[178:179], v[130:131]
	v_lshl_add_u64 v[146:147], v[146:147], 0, v[180:181]
	global_store_dwordx4 v[148:149], v[60:63], off sc1
	v_cvt_pk_bf16_f32 v130, v60, v61
	v_lshlrev_b64 v[132:133], 1, v[146:147]
	v_lshl_add_u64 v[146:147], s[26:27], 0, v[132:133]
	v_mul_f32_e32 v61, v61, v61
	v_fmac_f32_e32 v61, v60, v60
	v_mul_f32_e32 v60, v63, v63
	v_fmac_f32_e32 v60, v62, v62
	s_waitcnt vmcnt(15)
	v_pk_fma_f32 v[58:59], v[58:59], v[124:125], v[136:137]
	v_pk_fma_f32 v[56:57], v[56:57], v[178:179], v[134:135]
	v_cvt_pk_bf16_f32 v131, v62, v63
	global_store_dwordx2 v[146:147], v[130:131], off
	v_add_f32_e32 v129, v61, v60
	global_store_dwordx4 v[148:149], v[56:59], off offset:64 sc1
	v_cvt_pk_bf16_f32 v60, v56, v57
	v_or_b32_e32 v62, 32, v132
	v_mov_b32_e32 v63, v133
	v_mul_f32_e32 v57, v57, v57
	v_fmac_f32_e32 v57, v56, v56
	v_mul_f32_e32 v56, v59, v59
	v_fmac_f32_e32 v56, v58, v58
	v_lshl_add_u64 v[62:63], s[26:27], 0, v[62:63]
	v_add_f32_e32 v56, v57, v56
	s_waitcnt vmcnt(16)
	v_pk_fma_f32 v[54:55], v[54:55], v[124:125], v[140:141]
	v_pk_fma_f32 v[52:53], v[52:53], v[178:179], v[138:139]
	v_cvt_pk_bf16_f32 v61, v58, v59
	global_store_dwordx2 v[62:63], v[60:61], off
	v_add_f32_e32 v60, v129, v56
	global_store_dwordx4 v[148:149], v[52:55], off offset:512 sc1
	v_cvt_pk_bf16_f32 v56, v52, v53
	s_waitcnt vmcnt(17)
	v_pk_fma_f32 v[50:51], v[50:51], v[124:125], v[144:145]
	v_pk_fma_f32 v[48:49], v[48:49], v[178:179], v[142:143]
	v_mul_f32_e32 v53, v53, v53
	v_fmac_f32_e32 v53, v52, v52
	v_mul_f32_e32 v52, v55, v55
	v_fmac_f32_e32 v52, v54, v54
	v_cvt_pk_bf16_f32 v57, v54, v55
	v_add_f32_e32 v52, v53, v52
	v_mul_f32_e32 v53, v49, v49
	v_mul_f32_e32 v54, v51, v51
	v_fmac_f32_e32 v53, v48, v48
	v_fmac_f32_e32 v54, v50, v50
	v_add_f32_e32 v52, v60, v52
	v_add_f32_e32 v53, v53, v54
	v_add_f32_e32 v54, v52, v53
	ds_bpermute_b32 v55, v213, v54
	v_or_b32_e32 v58, 0x100, v132
	v_mov_b32_e32 v59, v133
	v_lshl_add_u64 v[52:53], s[26:27], 0, v[58:59]
	global_store_dwordx2 v[52:53], v[56:57], off
	global_store_dwordx4 v[148:149], v[48:51], off offset:576 sc1
	v_cvt_pk_bf16_f32 v52, v48, v49
	v_or_b32_e32 v132, 0x120, v132
	v_cvt_pk_bf16_f32 v53, v50, v51
	s_waitcnt lgkmcnt(0)
	v_add_f32_e32 v48, v54, v55
	ds_bpermute_b32 v49, v212, v48
	v_lshl_add_u64 v[50:51], s[26:27], 0, v[132:133]
	global_store_dwordx2 v[50:51], v[52:53], off
	s_and_saveexec_b64 s[2:3], vcc
	s_cbranch_execz .LBB0_1535
	s_waitcnt lgkmcnt(0)
	v_add_f32_e32 v48, v48, v49
	ds_write_b32 v128, v48 offset:2048
; __device__ __forceinline__ unsigned cvt_pk_bf16(float lo, float hi) { unsigned r; asm volatile("v_cvt_pk_bf16_f32 %0, %1, %2" : "=v"(r) : "v"(lo), "v"(hi)); return r; }
; __device__ __forceinline__ float bperm(float v, int srclane) { return __int_as_float(__builtin_amdgcn_ds_bpermute(srclane << 2, __float_as_int(v))); }
; __device__ __forceinline__ float bperm(float v, int srclane) { return __int_as_float(__builtin_amdgcn_ds_bpermute(srclane << 2, __float_as_int(v))); }
;     __device__ __forceinline__ void fused(f32x4 (&acc)[2][2][4][2], const Unit& u, int wr, int wc, int fr, int fq, PG8_LAS unsigned char* lds, int wid, int lane) const {
;     ...
;             for (int m = 0; m < 4; ++m) { const int row = row0 + ai * HALF + m * 16; float q = 0.f;
; #pragma unroll
;                 for (int bj = 0; bj < 2; ++bj)
; #pragma unroll
;                     for (int n = 0; n < 2; ++n) { const size_t off = (size_t)row * 1024 + col0 + bj * HALF + n * 16;
;                         f32x4 v = xv[m][bj][n] + acc[ai][bj][m][n] * scl; *(f32x4*)(x + off) = v;
;                         u32x2 w; w.x = cvt_pk_bf16(v[0], v[1]); w.y = cvt_pk_bf16(v[2], v[3]); *(u32x2*)(xb + off) = w;
;                         q += (v[0] * v[0] + v[1] * v[1]) + (v[2] * v[2] + v[3] * v[3]); }
;                 q += bperm(q, (fr + 16 * fq) ^ 16); q += bperm(q, (fr + 16 * fq) ^ 32);
;                 if (fq == 0) P[(ai * HALF + wr * 64 + m * 16 + fr) * 4 + wc] = q; }
.LBB0_1535:
	s_or_b64 exec, exec, s[2:3]
	s_waitcnt lgkmcnt(0)
	v_lshlrev_b64 v[48:49], 10, v[126:127]
	v_lshl_add_u64 v[50:51], v[48:49], 0, v[180:181]
	v_mov_b32_e32 v48, v178
	v_mov_b32_e32 v49, v178
	s_waitcnt vmcnt(19)
	v_pk_fma_f32 v[46:47], v[46:47], v[48:49], v[112:113]
	v_pk_fma_f32 v[44:45], v[44:45], v[178:179], v[110:111]
	global_store_dwordx4 v[122:123], v[44:47], off sc1
	v_cvt_pk_bf16_f32 v52, v44, v45
	v_lshlrev_b64 v[50:51], 1, v[50:51]
	v_lshl_add_u64 v[54:55], s[26:27], 0, v[50:51]
	v_mul_f32_e32 v45, v45, v45
	v_fmac_f32_e32 v45, v44, v44
	v_mul_f32_e32 v44, v47, v47
	v_fmac_f32_e32 v44, v46, v46
	s_waitcnt vmcnt(19)
	v_pk_fma_f32 v[42:43], v[42:43], v[48:49], v[108:109]
	v_pk_fma_f32 v[40:41], v[40:41], v[178:179], v[106:107]
	v_cvt_pk_bf16_f32 v53, v46, v47
	global_store_dwordx2 v[54:55], v[52:53], off
	v_add_f32_e32 v52, v45, v44
	global_store_dwordx4 v[122:123], v[40:43], off offset:64 sc1
	v_cvt_pk_bf16_f32 v44, v40, v41
	v_or_b32_e32 v46, 32, v50
	v_mov_b32_e32 v47, v51
	v_mul_f32_e32 v41, v41, v41
	v_fmac_f32_e32 v41, v40, v40
	v_mul_f32_e32 v40, v43, v43
	v_fmac_f32_e32 v40, v42, v42
	v_lshl_add_u64 v[46:47], s[26:27], 0, v[46:47]
	v_add_f32_e32 v40, v41, v40
	s_waitcnt vmcnt(20)
	v_pk_fma_f32 v[38:39], v[38:39], v[48:49], v[104:105]
	v_pk_fma_f32 v[36:37], v[36:37], v[178:179], v[102:103]
	v_cvt_pk_bf16_f32 v45, v42, v43
	global_store_dwordx2 v[46:47], v[44:45], off
	v_add_f32_e32 v44, v52, v40
	global_store_dwordx4 v[122:123], v[36:39], off offset:512 sc1
	v_cvt_pk_bf16_f32 v40, v36, v37
	s_waitcnt vmcnt(21)
	v_pk_fma_f32 v[34:35], v[34:35], v[48:49], v[100:101]
	v_pk_fma_f32 v[32:33], v[32:33], v[178:179], v[98:99]
	v_mul_f32_e32 v37, v37, v37
	v_fmac_f32_e32 v37, v36, v36
	v_mul_f32_e32 v36, v39, v39
	v_fmac_f32_e32 v36, v38, v38
	v_cvt_pk_bf16_f32 v41, v38, v39
	v_add_f32_e32 v36, v37, v36
	v_mul_f32_e32 v37, v33, v33
	v_mul_f32_e32 v38, v35, v35
	v_fmac_f32_e32 v37, v32, v32
	v_fmac_f32_e32 v38, v34, v34
	v_add_f32_e32 v36, v44, v36
	v_add_f32_e32 v37, v37, v38
	v_add_f32_e32 v38, v36, v37
	ds_bpermute_b32 v39, v213, v38
	v_or_b32_e32 v42, 0x100, v50
	v_mov_b32_e32 v43, v51
	v_lshl_add_u64 v[36:37], s[26:27], 0, v[42:43]
	global_store_dwordx2 v[36:37], v[40:41], off
	global_store_dwordx4 v[122:123], v[32:35], off offset:576 sc1
	v_cvt_pk_bf16_f32 v36, v32, v33
	v_or_b32_e32 v50, 0x120, v50
	v_cvt_pk_bf16_f32 v37, v34, v35
	s_waitcnt lgkmcnt(0)
	v_add_f32_e32 v32, v38, v39
	ds_bpermute_b32 v33, v212, v32
	v_lshl_add_u64 v[34:35], s[26:27], 0, v[50:51]
	global_store_dwordx2 v[34:35], v[36:37], off
	s_and_saveexec_b64 s[2:3], vcc
	s_cbranch_execz .LBB0_1537
	s_waitcnt lgkmcnt(0)
	v_add_f32_e32 v32, v32, v33
	ds_write_b32 v128, v32 offset:2304
; __device__ __forceinline__ unsigned cvt_pk_bf16(float lo, float hi) { unsigned r; asm volatile("v_cvt_pk_bf16_f32 %0, %1, %2" : "=v"(r) : "v"(lo), "v"(hi)); return r; }
; __device__ __forceinline__ float bperm(float v, int srclane) { return __int_as_float(__builtin_amdgcn_ds_bpermute(srclane << 2, __float_as_int(v))); }
; __device__ __forceinline__ float bperm(float v, int srclane) { return __int_as_float(__builtin_amdgcn_ds_bpermute(srclane << 2, __float_as_int(v))); }
;     __device__ __forceinline__ void fused(f32x4 (&acc)[2][2][4][2], const Unit& u, int wr, int wc, int fr, int fq, PG8_LAS unsigned char* lds, int wid, int lane) const {
;     ...
;             for (int m = 0; m < 4; ++m) { const int row = row0 + ai * HALF + m * 16; float q = 0.f;
; #pragma unroll
;                 for (int bj = 0; bj < 2; ++bj)
; #pragma unroll
;                     for (int n = 0; n < 2; ++n) { const size_t off = (size_t)row * 1024 + col0 + bj * HALF + n * 16;
;                         f32x4 v = xv[m][bj][n] + acc[ai][bj][m][n] * scl; *(f32x4*)(x + off) = v;
;                         u32x2 w; w.x = cvt_pk_bf16(v[0], v[1]); w.y = cvt_pk_bf16(v[2], v[3]); *(u32x2*)(xb + off) = w;
;                         q += (v[0] * v[0] + v[1] * v[1]) + (v[2] * v[2] + v[3] * v[3]); }
;                 q += bperm(q, (fr + 16 * fq) ^ 16); q += bperm(q, (fr + 16 * fq) ^ 32);
;                 if (fq == 0) P[(ai * HALF + wr * 64 + m * 16 + fr) * 4 + wc] = q; }
.LBB0_1537:
	s_or_b64 exec, exec, s[2:3]
	s_waitcnt lgkmcnt(0)
	v_lshlrev_b64 v[32:33], 10, v[120:121]
	s_waitcnt vmcnt(23)
	v_pk_fma_f32 v[30:31], v[30:31], v[48:49], v[96:97]
	v_pk_fma_f32 v[28:29], v[28:29], v[178:179], v[94:95]
	v_lshl_add_u64 v[32:33], v[32:33], 0, v[180:181]
	global_store_dwordx4 v[118:119], v[28:31], off sc1
	v_cvt_pk_bf16_f32 v34, v28, v29
	v_lshlrev_b64 v[32:33], 1, v[32:33]
	v_lshl_add_u64 v[36:37], s[26:27], 0, v[32:33]
	v_mul_f32_e32 v29, v29, v29
	v_fmac_f32_e32 v29, v28, v28
	v_mul_f32_e32 v28, v31, v31
	v_fmac_f32_e32 v28, v30, v30
	s_waitcnt vmcnt(23)
	v_pk_fma_f32 v[26:27], v[26:27], v[48:49], v[92:93]
	v_pk_fma_f32 v[24:25], v[24:25], v[178:179], v[90:91]
	v_cvt_pk_bf16_f32 v35, v30, v31
	global_store_dwordx2 v[36:37], v[34:35], off
	v_add_f32_e32 v34, v29, v28
	global_store_dwordx4 v[118:119], v[24:27], off offset:64 sc1
	v_cvt_pk_bf16_f32 v28, v24, v25
	v_or_b32_e32 v30, 32, v32
	v_mov_b32_e32 v31, v33
	v_mul_f32_e32 v25, v25, v25
	v_fmac_f32_e32 v25, v24, v24
	v_mul_f32_e32 v24, v27, v27
	v_fmac_f32_e32 v24, v26, v26
	v_lshl_add_u64 v[30:31], s[26:27], 0, v[30:31]
	v_add_f32_e32 v24, v25, v24
	s_waitcnt vmcnt(24)
	v_pk_fma_f32 v[22:23], v[22:23], v[48:49], v[88:89]
	v_pk_fma_f32 v[20:21], v[20:21], v[178:179], v[86:87]
	v_cvt_pk_bf16_f32 v29, v26, v27
	global_store_dwordx2 v[30:31], v[28:29], off
	v_add_f32_e32 v28, v34, v24
	global_store_dwordx4 v[118:119], v[20:23], off offset:512 sc1
	v_cvt_pk_bf16_f32 v24, v20, v21
	s_waitcnt vmcnt(25)
	v_pk_fma_f32 v[18:19], v[18:19], v[48:49], v[84:85]
	v_pk_fma_f32 v[16:17], v[16:17], v[178:179], v[82:83]
	v_mul_f32_e32 v21, v21, v21
	v_fmac_f32_e32 v21, v20, v20
	v_mul_f32_e32 v20, v23, v23
	v_fmac_f32_e32 v20, v22, v22
	v_cvt_pk_bf16_f32 v25, v22, v23
	v_add_f32_e32 v20, v21, v20
	v_mul_f32_e32 v21, v17, v17
	v_mul_f32_e32 v22, v19, v19
	v_fmac_f32_e32 v21, v16, v16
	v_fmac_f32_e32 v22, v18, v18
	v_add_f32_e32 v20, v28, v20
	v_add_f32_e32 v21, v21, v22
	v_add_f32_e32 v22, v20, v21
	ds_bpermute_b32 v23, v213, v22
	v_or_b32_e32 v26, 0x100, v32
	v_mov_b32_e32 v27, v33
	v_lshl_add_u64 v[20:21], s[26:27], 0, v[26:27]
	global_store_dwordx2 v[20:21], v[24:25], off
	global_store_dwordx4 v[118:119], v[16:19], off offset:576 sc1
	v_cvt_pk_bf16_f32 v20, v16, v17
	v_or_b32_e32 v32, 0x120, v32
	v_cvt_pk_bf16_f32 v21, v18, v19
	s_waitcnt lgkmcnt(0)
	v_add_f32_e32 v16, v22, v23
	ds_bpermute_b32 v17, v212, v16
	v_lshl_add_u64 v[18:19], s[26:27], 0, v[32:33]
	global_store_dwordx2 v[18:19], v[20:21], off
	s_and_saveexec_b64 s[2:3], vcc
	s_cbranch_execz .LBB0_1539
	s_waitcnt lgkmcnt(0)
	v_add_f32_e32 v16, v16, v17
	ds_write_b32 v128, v16 offset:2560
.LBB0_1539:
	s_or_b64 exec, exec, s[2:3]
	v_mov_b32_e32 v18, v178
	v_mov_b32_e32 v19, v178
	s_waitcnt lgkmcnt(0)
	v_lshlrev_b64 v[16:17], 10, v[116:117]
	s_waitcnt vmcnt(27)
	v_pk_fma_f32 v[14:15], v[14:15], v[18:19], v[80:81]
	v_pk_fma_f32 v[12:13], v[12:13], v[178:179], v[78:79]
	v_lshl_add_u64 v[16:17], v[16:17], 0, v[180:181]
	global_store_dwordx4 v[114:115], v[12:15], off sc1
	v_cvt_pk_bf16_f32 v20, v12, v13
	v_lshlrev_b64 v[16:17], 1, v[16:17]
	v_lshl_add_u64 v[22:23], s[26:27], 0, v[16:17]
	v_mul_f32_e32 v13, v13, v13
	v_fmac_f32_e32 v13, v12, v12
	v_mul_f32_e32 v12, v15, v15
	v_fmac_f32_e32 v12, v14, v14
	s_waitcnt vmcnt(27)
	v_pk_fma_f32 v[10:11], v[10:11], v[18:19], v[76:77]
	v_pk_fma_f32 v[8:9], v[8:9], v[178:179], v[74:75]
	v_cvt_pk_bf16_f32 v21, v14, v15
	global_store_dwordx2 v[22:23], v[20:21], off
	v_add_f32_e32 v20, v13, v12
	global_store_dwordx4 v[114:115], v[8:11], off offset:64 sc1
	v_cvt_pk_bf16_f32 v12, v8, v9
	v_or_b32_e32 v14, 32, v16
	v_mov_b32_e32 v15, v17
	v_mul_f32_e32 v9, v9, v9
	v_fmac_f32_e32 v9, v8, v8
	v_mul_f32_e32 v8, v11, v11
	v_fmac_f32_e32 v8, v10, v10
	v_lshl_add_u64 v[14:15], s[26:27], 0, v[14:15]
	v_add_f32_e32 v8, v9, v8
	s_waitcnt vmcnt(28)
	v_pk_fma_f32 v[6:7], v[6:7], v[18:19], v[72:73]
	v_pk_fma_f32 v[4:5], v[4:5], v[178:179], v[70:71]
	v_cvt_pk_bf16_f32 v13, v10, v11
	global_store_dwordx2 v[14:15], v[12:13], off
	v_add_f32_e32 v12, v20, v8
	global_store_dwordx4 v[114:115], v[4:7], off offset:512 sc1
	v_cvt_pk_bf16_f32 v8, v4, v5
	s_waitcnt vmcnt(29)
	v_pk_fma_f32 v[2:3], v[2:3], v[18:19], v[68:69]
	v_pk_fma_f32 v[0:1], v[0:1], v[178:179], v[66:67]
	v_mul_f32_e32 v5, v5, v5
	v_fmac_f32_e32 v5, v4, v4
	v_mul_f32_e32 v4, v7, v7
	v_fmac_f32_e32 v4, v6, v6
	v_cvt_pk_bf16_f32 v9, v6, v7
	v_add_f32_e32 v4, v5, v4
	v_mul_f32_e32 v5, v1, v1
	v_mul_f32_e32 v6, v3, v3
	v_fmac_f32_e32 v5, v0, v0
	v_fmac_f32_e32 v6, v2, v2
	v_add_f32_e32 v4, v12, v4
	v_add_f32_e32 v5, v5, v6
	v_add_f32_e32 v6, v4, v5
	ds_bpermute_b32 v7, v213, v6
	v_or_b32_e32 v10, 0x100, v16
	v_mov_b32_e32 v11, v17
	v_lshl_add_u64 v[4:5], s[26:27], 0, v[10:11]
	global_store_dwordx2 v[4:5], v[8:9], off
	global_store_dwordx4 v[114:115], v[0:3], off offset:576 sc1
	v_cvt_pk_bf16_f32 v4, v0, v1
	v_or_b32_e32 v16, 0x120, v16
	v_cvt_pk_bf16_f32 v5, v2, v3
	s_waitcnt lgkmcnt(0)
	v_add_f32_e32 v0, v6, v7
	ds_bpermute_b32 v1, v212, v0
	v_lshl_add_u64 v[2:3], s[26:27], 0, v[16:17]
	global_store_dwordx2 v[2:3], v[4:5], off
	s_and_saveexec_b64 s[2:3], vcc
	s_cbranch_execz .LBB0_1541
	s_waitcnt lgkmcnt(0)
	v_add_f32_e32 v0, v0, v1
	ds_write_b32 v128, v0 offset:2816
